# P6: every wave 4 prompt rows; sample rows handled cooperatively by the 8 waves of workgroup bx<128 (256 columns each, LDS exchange of row statistics)
# speedup vs baseline: 1.0343x; 1.0026x over previous
.LBB0_738:
	s_or_b64 exec, exec, s[4:5]
	v_mov_b32_e32 v95, 0
	v_lshlrev_b32_e32 v94, 4, v170
	v_lshl_add_u64 v[34:35], s[50:51], 0, v[94:95]
	s_movk_i32 s0, 0x1000
	v_add_co_u32_e32 v54, vcc, s0, v34
	v_lshl_add_u64 v[36:37], s[16:17], 0, v[94:95]
	s_nop 0
	v_addc_co_u32_e32 v55, vcc, 0, v35, vcc
	v_add_co_u32_e32 v62, vcc, s0, v36
	s_cmpk_lg_i32 s96, 0x100
	s_nop 0
	v_addc_co_u32_e32 v63, vcc, 0, v37, vcc
	s_cselect_b64 s[12:13], -1, 0
	s_add_i32 s1, s34, 0x207f
	s_and_b32 s3, s68, 15
	s_waitcnt lgkmcnt(0)
	s_barrier
	global_load_dwordx4 v[2:5], v94, s[50:51]
	global_load_dwordx4 v[6:9], v94, s[50:51] offset:1024
	global_load_dwordx4 v[10:13], v94, s[16:17]
	global_load_dwordx4 v[14:17], v94, s[16:17] offset:1024
	global_load_dwordx4 v[18:21], v94, s[50:51] offset:2048
	global_load_dwordx4 v[22:25], v94, s[50:51] offset:3072
	global_load_dwordx4 v[26:29], v94, s[16:17] offset:2048
	global_load_dwordx4 v[30:33], v94, s[16:17] offset:3072
	global_load_dwordx4 v[34:37], v[54:55], off
	global_load_dwordx4 v[38:41], v[54:55], off offset:1024
	global_load_dwordx4 v[42:45], v[62:63], off
	global_load_dwordx4 v[46:49], v[62:63], off offset:1024
	global_load_dwordx4 v[50:53], v[54:55], off offset:2048
	s_nop 0
	global_load_dwordx4 v[54:57], v[54:55], off offset:3072
	s_nop 0
	global_load_dwordx4 v[58:61], v[62:63], off offset:2048
	s_nop 0
	global_load_dwordx4 v[62:65], v[62:63], off offset:3072
	s_cmp_eq_u32 s3, 0
	s_cselect_b64 s[4:5], -1, 0
	s_ashr_i32 s8, s68, 4
	s_cmpk_lt_i32 s8, 0x80
	s_cselect_b64 s[6:7], -1, 0
	s_and_b64 s[4:5], s[4:5], s[6:7]
	s_cmp_eq_u32 s3, 8
	s_cselect_b64 s[6:7], -1, 0
	s_cmpk_lt_i32 s68, 0x808
	s_mul_i32 s3, s96, 24
	s_cselect_b64 s[10:11], -1, 0
	s_add_i32 s3, s3, s68
	s_and_b64 s[6:7], s[10:11], s[6:7]
	s_add_i32 s10, s3, -8
	s_and_b64 s[6:7], s[6:7], exec
	s_cselect_b32 s69, s10, -1
	s_addk_i32 s8, 0x2000
	s_and_b64 s[4:5], s[4:5], exec
	s_cselect_b32 s72, s8, s3
	v_or_b32_e32 v66, 0x1000, v171
	s_mov_b32 s3, 0x5555556
	v_mul_hi_u32 v67, v66, s3
	v_lshl_add_u32 v98, v67, 4, v66
	v_or_b32_e32 v66, 0x1100, v171
	v_mul_hi_u32 v67, v66, s3
	v_lshl_add_u32 v100, v67, 4, v66
	v_or_b32_e32 v66, 0x1200, v171
	v_mul_hi_u32 v67, v66, s3
	v_lshl_add_u32 v102, v67, 4, v66
	v_or_b32_e32 v66, 0x1300, v171
	v_mul_hi_u32 v67, v66, s3
	v_lshl_add_u32 v104, v67, 4, v66
	v_or_b32_e32 v66, 0x1400, v171
	v_mul_hi_u32 v67, v66, s3
	v_lshl_add_u32 v106, v67, 4, v66
	v_or_b32_e32 v66, 0x1500, v171
	v_mul_hi_u32 v67, v66, s3
	v_lshl_add_u32 v108, v67, 4, v66
	v_or_b32_e32 v66, 0x1600, v171
	v_mul_hi_u32 v67, v66, s3
	v_lshl_add_u32 v110, v67, 4, v66
	v_or_b32_e32 v66, 0x1700, v171
	v_mul_hi_u32 v67, v66, s3
	v_lshl_add_u32 v112, v67, 4, v66
	v_or_b32_e32 v66, 0x2000, v171
	v_mul_hi_u32 v67, v66, s3
	v_lshl_add_u32 v116, v67, 4, v66
	v_or_b32_e32 v66, 0x1800, v171
	v_mul_hi_u32 v67, v66, s3
	v_lshl_add_u32 v118, v67, 4, v66
	v_or_b32_e32 v66, 0x2100, v171
	v_mul_hi_u32 v67, v66, s3
	v_lshl_add_u32 v120, v67, 4, v66
	v_or_b32_e32 v66, 0x1900, v171
	v_mul_hi_u32 v67, v66, s3
	v_lshl_add_u32 v122, v67, 4, v66
	v_or_b32_e32 v66, 0x2200, v171
	v_mul_hi_u32 v67, v66, s3
	v_lshl_add_u32 v124, v67, 4, v66
	v_or_b32_e32 v66, 0x1a00, v171
	v_mul_hi_u32 v67, v66, s3
	v_lshl_add_u32 v126, v67, 4, v66
	v_or_b32_e32 v66, 0x2300, v171
	v_mul_hi_u32 v67, v66, s3
	v_lshl_add_u32 v128, v67, 4, v66
	v_or_b32_e32 v66, 0x1b00, v171
	v_mul_hi_u32 v67, v66, s3
	v_lshl_add_u32 v130, v67, 4, v66
	v_or_b32_e32 v66, 0x2400, v171
	v_mul_hi_u32 v67, v66, s3
	v_lshl_add_u32 v132, v67, 4, v66
	v_or_b32_e32 v66, 0x1c00, v171
	v_mul_hi_u32 v67, v66, s3
	v_lshl_add_u32 v134, v67, 4, v66
	v_or_b32_e32 v66, 0x2500, v171
	v_mul_hi_u32 v67, v66, s3
	v_lshl_add_u32 v136, v67, 4, v66
	v_or_b32_e32 v66, 0x1d00, v171
	v_mul_hi_u32 v67, v66, s3
	v_lshl_add_u32 v138, v67, 4, v66
	v_or_b32_e32 v66, 0x2600, v171
	v_lshl_add_u64 v[174:175], s[42:43], 0, v[94:95]
	s_mov_b64 s[4:5], 0x1000
	v_mul_hi_u32 v67, v66, s3
	v_lshl_add_u64 v[176:177], v[174:175], 0, s[4:5]
	s_mov_b64 s[4:5], 0x1400
	v_lshl_add_u32 v140, v67, 4, v66
	v_or_b32_e32 v66, 0x1e00, v171
	v_lshl_add_u64 v[178:179], v[174:175], 0, s[4:5]
	s_mov_b64 s[4:5], 0x1800
	v_mul_hi_u32 v67, v66, s3
	v_lshl_add_u64 v[180:181], v[174:175], 0, s[4:5]
	s_mov_b64 s[4:5], 0x1c00
	v_lshl_add_u32 v142, v67, 4, v66
	v_or_b32_e32 v66, 0x2700, v171
	v_lshl_add_u64 v[182:183], v[174:175], 0, s[4:5]
	v_mul_hi_u32 v67, v66, s3
	s_abs_i32 s4, s34
	v_lshl_add_u32 v144, v67, 4, v66
	v_cvt_f32_u32_e32 v66, s4
	s_sub_i32 s5, 0, s4
	v_or_b32_e32 v67, 0x1f00, v171
	v_mul_hi_u32 v68, v67, s3
	v_rcp_iflag_f32_e32 v66, v66
	s_xor_b32 s3, s1, s34
	s_abs_i32 s1, s1
	s_ashr_i32 s3, s3, 31
	v_mul_f32_e32 v66, 0x4f7ffffe, v66
	v_cvt_u32_f32_e32 v66, v66
	v_mov_b32_e32 v159, v95
	s_mov_b32 s9, 0
	v_lshl_add_u64 v[96:97], s[44:45], 0, v[158:159]
	v_readfirstlane_b32 s6, v66
	s_mul_i32 s5, s5, s6
	s_mul_hi_u32 s5, s6, s5
	s_add_i32 s6, s6, s5
	s_mul_hi_u32 s5, s1, s6
	s_mul_i32 s6, s5, s4
	s_sub_i32 s1, s1, s6
	s_add_i32 s6, s5, 1
	s_sub_i32 s7, s1, s4
	s_cmp_ge_u32 s1, s4
	s_cselect_b32 s5, s6, s5
	s_cselect_b32 s1, s7, s1
	s_add_i32 s6, s5, 1
	s_cmp_ge_u32 s1, s4
	s_cselect_b32 s1, s6, s5
	s_xor_b32 s1, s1, s3
	v_mbcnt_lo_u32_b32 v66, -1, 0
	v_lshl_add_u64 v[172:173], s[40:41], 0, v[94:95]
	v_mov_b32_e32 v99, v95
	v_mov_b32_e32 v101, v95
	v_mov_b32_e32 v103, v95
	v_mov_b32_e32 v105, v95
	v_mov_b32_e32 v107, v95
	v_mov_b32_e32 v109, v95
	v_mov_b32_e32 v111, v95
	v_mov_b32_e32 v113, v95
	v_lshl_add_u64 v[114:115], s[54:55], 0, v[94:95]
	v_mov_b32_e32 v117, v95
	v_mov_b32_e32 v119, v95
	v_mov_b32_e32 v121, v95
	v_mov_b32_e32 v123, v95
	v_mov_b32_e32 v125, v95
	v_mov_b32_e32 v127, v95
	v_mov_b32_e32 v129, v95
	v_mov_b32_e32 v131, v95
	v_mov_b32_e32 v133, v95
	v_mov_b32_e32 v135, v95
	v_mov_b32_e32 v137, v95
	v_mov_b32_e32 v139, v95
	v_mov_b32_e32 v141, v95
	v_mov_b32_e32 v143, v95
	v_mov_b32_e32 v145, v95
	v_lshl_add_u32 v146, v68, 4, v67
	v_mov_b32_e32 v147, v95
	s_sub_i32 s73, s1, s3
	s_mov_b32 s1, 0x100000
	s_mov_b32 s3, 0x200000
	s_mov_b32 s10, 0x300000
	s_mov_b32 s11, 0x400000
	s_mov_b32 s17, 0x500000
	s_mov_b32 s50, 0x600000
	s_mov_b32 s51, 0x700000
	s_mov_b32 s16, 0x3f9837f0
	v_mov_b32_e32 v151, 0x3727c5ac
	s_mov_b32 s54, 0xf800000
	v_mov_b32_e32 v153, 0x260
	s_movk_i32 s55, 0x7fff
	s_mov_b32 s56, 0xffff0000
	v_mov_b32_e32 v155, 0x2000
	v_mov_b32_e32 v157, 0x207f
	v_mbcnt_hi_u32_b32 v211, -1, v66
	s_mov_b32 s57, s68
	s_mov_b32 s58, s68
	s_mov_b32 s59, 0
	v_cndmask_b32_e64 v66, 0, 1, s[12:13]
	v_cmp_ne_u32_e64 s[4:5], 1, v66
	s_mov_b32 s3, 0x3f9837f0
	v_lshlrev_b32_e32 v129, 4, v170
	v_add_u32_e32 v131, 0x1000, v129
	v_lshlrev_b32_e32 v117, 3, v170
	v_xor_b32_e32 v99, 1, v211
	v_lshlrev_b32_e32 v99, 2, v99
	v_xor_b32_e32 v101, 2, v211
	v_lshlrev_b32_e32 v101, 2, v101
	v_xor_b32_e32 v103, 4, v211
	v_lshlrev_b32_e32 v103, 2, v103
	v_xor_b32_e32 v105, 8, v211
	v_lshlrev_b32_e32 v105, 2, v105
	v_xor_b32_e32 v107, 16, v211
	v_lshlrev_b32_e32 v107, 2, v107
	v_xor_b32_e32 v119, 32, v211
	v_lshlrev_b32_e32 v119, 2, v119
	s_mov_b32 s0, s68
	s_lshl_b32 s1, s0, 13
	s_add_u32 s6, s40, s1
	s_addc_u32 s7, s41, 0
	s_lshl_b32 s1, s0, 12
	s_add_u32 s10, s44, s1
	s_addc_u32 s11, s45, 0
	s_lshr_b32 s1, s0, 11
	s_lshl_b32 s1, s1, 16
	s_add_u32 s16, s14, s1
	s_addc_u32 s17, s15, 0
	global_load_dwordx4 v[66:69], v129, s[6:7]
	global_load_dwordx4 v[70:73], v129, s[6:7] offset:1024
	global_load_dwordx4 v[74:77], v129, s[6:7] offset:2048
	global_load_dwordx4 v[78:81], v129, s[6:7] offset:3072
	global_load_dwordx4 v[82:85], v131, s[6:7]
	global_load_dwordx4 v[86:89], v131, s[6:7] offset:1024
	global_load_dwordx4 v[90:93], v131, s[6:7] offset:2048
	global_load_dwordx4 v[94:97], v131, s[6:7] offset:3072
	v_lshlrev_b32_e32 v151, 2, v116
	global_load_dwordx4 v[158:161], v151, s[16:17]
	v_lshlrev_b32_e32 v151, 2, v118
	global_load_dwordx4 v[220:223], v151, s[16:17]
	v_lshlrev_b32_e32 v151, 2, v120
	global_load_dwordx4 v[162:165], v151, s[16:17]
	v_lshlrev_b32_e32 v151, 2, v122
	global_load_dwordx4 v[224:227], v151, s[16:17]
	v_lshlrev_b32_e32 v151, 2, v124
	global_load_dwordx4 v[166:169], v151, s[16:17]
	v_lshlrev_b32_e32 v151, 2, v126
	global_load_dwordx4 v[228:231], v151, s[16:17]
	v_lshlrev_b32_e32 v151, 2, v128
	global_load_dwordx4 v[176:179], v151, s[16:17]
	v_lshlrev_b32_e32 v151, 2, v130
	global_load_dwordx4 v[232:235], v151, s[16:17]
	v_lshlrev_b32_e32 v151, 2, v132
	global_load_dwordx4 v[180:183], v151, s[16:17]
	v_lshlrev_b32_e32 v151, 2, v134
	global_load_dwordx4 v[236:239], v151, s[16:17]
	v_lshlrev_b32_e32 v151, 2, v136
	global_load_dwordx4 v[184:187], v151, s[16:17]
	v_lshlrev_b32_e32 v151, 2, v138
	global_load_dwordx4 v[240:243], v151, s[16:17]
	v_lshlrev_b32_e32 v151, 2, v140
	global_load_dwordx4 v[212:215], v151, s[16:17]
	v_lshlrev_b32_e32 v151, 2, v142
	global_load_dwordx4 v[244:247], v151, s[16:17]
	v_lshlrev_b32_e32 v151, 2, v144
	global_load_dwordx4 v[216:219], v151, s[16:17]
	v_lshlrev_b32_e32 v151, 2, v146
	global_load_dwordx4 v[248:251], v151, s[16:17]
	s_waitcnt vmcnt(23)
	v_add_f32_e32 v151, v66, v67
	v_add_f32_e32 v155, v68, v69
	v_add_f32_e32 v151, v151, v155
	v_add_f32_e32 v153, 0, v151
	s_waitcnt vmcnt(22)
	v_add_f32_e32 v151, v70, v71
	v_add_f32_e32 v155, v72, v73
	v_add_f32_e32 v151, v151, v155
	v_add_f32_e32 v153, v153, v151
	s_waitcnt vmcnt(21)
	v_add_f32_e32 v151, v74, v75
	v_add_f32_e32 v155, v76, v77
	v_add_f32_e32 v151, v151, v155
	v_add_f32_e32 v153, v153, v151
	s_waitcnt vmcnt(20)
	v_add_f32_e32 v151, v78, v79
	v_add_f32_e32 v155, v80, v81
	v_add_f32_e32 v151, v151, v155
	v_add_f32_e32 v153, v153, v151
	s_waitcnt vmcnt(19)
	v_add_f32_e32 v151, v82, v83
	v_add_f32_e32 v155, v84, v85
	v_add_f32_e32 v151, v151, v155
	v_add_f32_e32 v153, v153, v151
	s_waitcnt vmcnt(18)
	v_add_f32_e32 v151, v86, v87
	v_add_f32_e32 v155, v88, v89
	v_add_f32_e32 v151, v151, v155
	v_add_f32_e32 v153, v153, v151
	s_waitcnt vmcnt(17)
	v_add_f32_e32 v151, v90, v91
	v_add_f32_e32 v155, v92, v93
	v_add_f32_e32 v151, v151, v155
	v_add_f32_e32 v153, v153, v151
	s_waitcnt vmcnt(16)
	v_add_f32_e32 v151, v94, v95
	v_add_f32_e32 v155, v96, v97
	v_add_f32_e32 v151, v151, v155
	v_add_f32_e32 v153, v153, v151
	ds_bpermute_b32 v151, v99, v153
	s_waitcnt lgkmcnt(0)
	v_add_f32_e32 v153, v153, v151
	ds_bpermute_b32 v151, v101, v153
	s_waitcnt lgkmcnt(0)
	v_add_f32_e32 v153, v153, v151
	ds_bpermute_b32 v151, v103, v153
	s_waitcnt lgkmcnt(0)
	v_add_f32_e32 v153, v153, v151
	ds_bpermute_b32 v151, v105, v153
	s_waitcnt lgkmcnt(0)
	v_add_f32_e32 v153, v153, v151
	ds_bpermute_b32 v151, v107, v153
	s_waitcnt lgkmcnt(0)
	v_add_f32_e32 v153, v153, v151
	ds_bpermute_b32 v151, v119, v153
	s_waitcnt lgkmcnt(0)
	v_add_f32_e32 v153, v153, v151
	v_fmac_f32_e32 v66, 0xba000000, v153
	v_fmac_f32_e32 v67, 0xba000000, v153
	v_fmac_f32_e32 v68, 0xba000000, v153
	v_fmac_f32_e32 v69, 0xba000000, v153
	v_fmac_f32_e32 v70, 0xba000000, v153
	v_fmac_f32_e32 v71, 0xba000000, v153
	v_fmac_f32_e32 v72, 0xba000000, v153
	v_fmac_f32_e32 v73, 0xba000000, v153
	v_fmac_f32_e32 v74, 0xba000000, v153
	v_fmac_f32_e32 v75, 0xba000000, v153
	v_fmac_f32_e32 v76, 0xba000000, v153
	v_fmac_f32_e32 v77, 0xba000000, v153
	v_fmac_f32_e32 v78, 0xba000000, v153
	v_fmac_f32_e32 v79, 0xba000000, v153
	v_fmac_f32_e32 v80, 0xba000000, v153
	v_fmac_f32_e32 v81, 0xba000000, v153
	v_fmac_f32_e32 v82, 0xba000000, v153
	v_fmac_f32_e32 v83, 0xba000000, v153
	v_fmac_f32_e32 v84, 0xba000000, v153
	v_fmac_f32_e32 v85, 0xba000000, v153
	v_fmac_f32_e32 v86, 0xba000000, v153
	v_fmac_f32_e32 v87, 0xba000000, v153
	v_fmac_f32_e32 v88, 0xba000000, v153
	v_fmac_f32_e32 v89, 0xba000000, v153
	v_fmac_f32_e32 v90, 0xba000000, v153
	v_fmac_f32_e32 v91, 0xba000000, v153
	v_fmac_f32_e32 v92, 0xba000000, v153
	v_fmac_f32_e32 v93, 0xba000000, v153
	v_fmac_f32_e32 v94, 0xba000000, v153
	v_fmac_f32_e32 v95, 0xba000000, v153
	v_fmac_f32_e32 v96, 0xba000000, v153
	v_fmac_f32_e32 v97, 0xba000000, v153
	v_mul_f32_e32 v151, v67, v67
	v_fma_f32 v151, v66, v66, v151
	v_mul_f32_e32 v155, v69, v69
	v_fma_f32 v155, v68, v68, v155
	v_add_f32_e32 v151, v151, v155
	v_add_f32_e32 v157, 0, v151
	v_mul_f32_e32 v151, v71, v71
	v_fma_f32 v151, v70, v70, v151
	v_mul_f32_e32 v155, v73, v73
	v_fma_f32 v155, v72, v72, v155
	v_add_f32_e32 v151, v151, v155
	v_add_f32_e32 v157, v157, v151
	v_mul_f32_e32 v151, v75, v75
	v_fma_f32 v151, v74, v74, v151
	v_mul_f32_e32 v155, v77, v77
	v_fma_f32 v155, v76, v76, v155
	v_add_f32_e32 v151, v151, v155
	v_add_f32_e32 v157, v157, v151
	v_mul_f32_e32 v151, v79, v79
	v_fma_f32 v151, v78, v78, v151
	v_mul_f32_e32 v155, v81, v81
	v_fma_f32 v155, v80, v80, v155
	v_add_f32_e32 v151, v151, v155
	v_add_f32_e32 v157, v157, v151
	v_mul_f32_e32 v151, v83, v83
	v_fma_f32 v151, v82, v82, v151
	v_mul_f32_e32 v155, v85, v85
	v_fma_f32 v155, v84, v84, v155
	v_add_f32_e32 v151, v151, v155
	v_add_f32_e32 v157, v157, v151
	v_mul_f32_e32 v151, v87, v87
	v_fma_f32 v151, v86, v86, v151
	v_mul_f32_e32 v155, v89, v89
	v_fma_f32 v155, v88, v88, v155
	v_add_f32_e32 v151, v151, v155
	v_add_f32_e32 v157, v157, v151
	v_mul_f32_e32 v151, v91, v91
	v_fma_f32 v151, v90, v90, v151
	v_mul_f32_e32 v155, v93, v93
	v_fma_f32 v155, v92, v92, v155
	v_add_f32_e32 v151, v151, v155
	v_add_f32_e32 v157, v157, v151
	v_mul_f32_e32 v151, v95, v95
	v_fma_f32 v151, v94, v94, v151
	v_mul_f32_e32 v155, v97, v97
	v_fma_f32 v155, v96, v96, v155
	v_add_f32_e32 v151, v151, v155
	v_add_f32_e32 v157, v157, v151
	ds_bpermute_b32 v151, v99, v157
	s_waitcnt lgkmcnt(0)
	v_add_f32_e32 v157, v157, v151
	ds_bpermute_b32 v151, v101, v157
	s_waitcnt lgkmcnt(0)
	v_add_f32_e32 v157, v157, v151
	ds_bpermute_b32 v151, v103, v157
	s_waitcnt lgkmcnt(0)
	v_add_f32_e32 v157, v157, v151
	ds_bpermute_b32 v151, v105, v157
	s_waitcnt lgkmcnt(0)
	v_add_f32_e32 v157, v157, v151
	ds_bpermute_b32 v151, v107, v157
	s_waitcnt lgkmcnt(0)
	v_add_f32_e32 v157, v157, v151
	ds_bpermute_b32 v151, v119, v157
	s_waitcnt lgkmcnt(0)
	v_add_f32_e32 v157, v157, v151
	v_mov_b32_e32 v254, 0x3727c5ac
	v_fmamk_f32 v157, v157, 0x3a000000, v254
	v_mul_f32_e32 v151, 0x4f800000, v157
	s_mov_b32 s9, 0xf800000
	v_cmp_gt_f32_e32 vcc, s9, v157
	s_nop 1
	v_cndmask_b32_e32 v157, v157, v151, vcc
	v_sqrt_f32_e32 v151, v157
	s_nop 0
	v_add_u32_e32 v203, -1, v151
	v_fma_f32 v204, -v203, v151, v157
	v_cmp_ge_f32_e64 s[88:89], 0, v204
	v_add_u32_e32 v204, 1, v151
	s_nop 0
	v_cndmask_b32_e64 v203, v151, v203, s[88:89]
	v_fma_f32 v151, -v204, v151, v157
	v_cmp_lt_f32_e64 s[88:89], 0, v151
	s_nop 1
	v_cndmask_b32_e64 v151, v203, v204, s[88:89]
	v_mul_f32_e32 v203, 0x37800000, v151
	v_cndmask_b32_e32 v151, v151, v203, vcc
	v_mov_b32_e32 v203, 0x260
	v_cmp_class_f32_e32 vcc, v157, v203
	s_nop 1
	v_cndmask_b32_e32 v157, v151, v157, vcc
	v_div_scale_f32 v151, s[88:89], v157, v157, 1.0
	v_rcp_f32_e32 v203, v151
	s_nop 0
	v_fma_f32 v204, -v151, v203, 1.0
	v_fmac_f32_e32 v203, v204, v203
	v_div_scale_f32 v204, vcc, 1.0, v157, 1.0
	v_mul_f32_e32 v205, v204, v203
	v_fma_f32 v254, -v151, v205, v204
	v_fmac_f32_e32 v205, v254, v203
	v_fma_f32 v151, -v151, v205, v204
	v_div_fmas_f32 v151, v151, v203, v205
	v_div_fixup_f32 v155, v151, v157, 1.0
	v_mul_f32_e32 v66, v66, v155
	v_mul_f32_e32 v67, v67, v155
	v_mul_f32_e32 v68, v68, v155
	v_mul_f32_e32 v69, v69, v155
	v_pk_fma_f32 v[66:67], v[2:3], v[66:67], v[10:11]
	v_pk_fma_f32 v[68:69], v[4:5], v[68:69], v[12:13]
	global_store_dwordx4 v129, v[66:69], s[6:7]
	s_waitcnt vmcnt(15)
	v_pk_add_f32 v[158:159], v[158:159], 1.0 op_sel_hi:[1,0]
	v_pk_add_f32 v[160:161], v[160:161], 1.0 op_sel_hi:[1,0]
	v_pk_fma_f32 v[158:159], v[158:159], v[66:67], v[220:221]
	v_pk_fma_f32 v[160:161], v[160:161], v[68:69], v[222:223]
	v_cvt_pk_bf16_f32 v158, v158, v159
	v_cvt_pk_bf16_f32 v159, v160, v161
	global_store_dwordx2 v117, v[158:159], s[10:11]
	v_mul_f32_e32 v70, v70, v155
	v_mul_f32_e32 v71, v71, v155
	v_mul_f32_e32 v72, v72, v155
	v_mul_f32_e32 v73, v73, v155
	v_pk_fma_f32 v[70:71], v[6:7], v[70:71], v[14:15]
	v_pk_fma_f32 v[72:73], v[8:9], v[72:73], v[16:17]
	global_store_dwordx4 v129, v[70:73], s[6:7] offset:1024
	s_waitcnt vmcnt(15)
	v_pk_add_f32 v[162:163], v[162:163], 1.0 op_sel_hi:[1,0]
	v_pk_add_f32 v[164:165], v[164:165], 1.0 op_sel_hi:[1,0]
	v_pk_fma_f32 v[162:163], v[162:163], v[70:71], v[224:225]
	v_pk_fma_f32 v[164:165], v[164:165], v[72:73], v[226:227]
	v_cvt_pk_bf16_f32 v162, v162, v163
	v_cvt_pk_bf16_f32 v163, v164, v165
	global_store_dwordx2 v117, v[162:163], s[10:11] offset:512
	v_mul_f32_e32 v74, v74, v155
	v_mul_f32_e32 v75, v75, v155
	v_mul_f32_e32 v76, v76, v155
	v_mul_f32_e32 v77, v77, v155
	v_pk_fma_f32 v[74:75], v[18:19], v[74:75], v[26:27]
	v_pk_fma_f32 v[76:77], v[20:21], v[76:77], v[28:29]
	global_store_dwordx4 v129, v[74:77], s[6:7] offset:2048
	s_waitcnt vmcnt(15)
	v_pk_add_f32 v[166:167], v[166:167], 1.0 op_sel_hi:[1,0]
	v_pk_add_f32 v[168:169], v[168:169], 1.0 op_sel_hi:[1,0]
	v_pk_fma_f32 v[166:167], v[166:167], v[74:75], v[228:229]
	v_pk_fma_f32 v[168:169], v[168:169], v[76:77], v[230:231]
	v_cvt_pk_bf16_f32 v166, v166, v167
	v_cvt_pk_bf16_f32 v167, v168, v169
	global_store_dwordx2 v117, v[166:167], s[10:11] offset:1024
	v_mul_f32_e32 v78, v78, v155
	v_mul_f32_e32 v79, v79, v155
	v_mul_f32_e32 v80, v80, v155
	v_mul_f32_e32 v81, v81, v155
	v_pk_fma_f32 v[78:79], v[22:23], v[78:79], v[30:31]
	v_pk_fma_f32 v[80:81], v[24:25], v[80:81], v[32:33]
	global_store_dwordx4 v129, v[78:81], s[6:7] offset:3072
	s_waitcnt vmcnt(15)
	v_pk_add_f32 v[176:177], v[176:177], 1.0 op_sel_hi:[1,0]
	v_pk_add_f32 v[178:179], v[178:179], 1.0 op_sel_hi:[1,0]
	v_pk_fma_f32 v[176:177], v[176:177], v[78:79], v[232:233]
	v_pk_fma_f32 v[178:179], v[178:179], v[80:81], v[234:235]
	v_cvt_pk_bf16_f32 v176, v176, v177
	v_cvt_pk_bf16_f32 v177, v178, v179
	global_store_dwordx2 v117, v[176:177], s[10:11] offset:1536
	v_mul_f32_e32 v82, v82, v155
	v_mul_f32_e32 v83, v83, v155
	v_mul_f32_e32 v84, v84, v155
	v_mul_f32_e32 v85, v85, v155
	v_pk_fma_f32 v[82:83], v[34:35], v[82:83], v[42:43]
	v_pk_fma_f32 v[84:85], v[36:37], v[84:85], v[44:45]
	global_store_dwordx4 v131, v[82:85], s[6:7]
	s_waitcnt vmcnt(15)
	v_pk_add_f32 v[180:181], v[180:181], 1.0 op_sel_hi:[1,0]
	v_pk_add_f32 v[182:183], v[182:183], 1.0 op_sel_hi:[1,0]
	v_pk_fma_f32 v[180:181], v[180:181], v[82:83], v[236:237]
	v_pk_fma_f32 v[182:183], v[182:183], v[84:85], v[238:239]
	v_cvt_pk_bf16_f32 v180, v180, v181
	v_cvt_pk_bf16_f32 v181, v182, v183
	global_store_dwordx2 v117, v[180:181], s[10:11] offset:2048
	v_mul_f32_e32 v86, v86, v155
	v_mul_f32_e32 v87, v87, v155
	v_mul_f32_e32 v88, v88, v155
	v_mul_f32_e32 v89, v89, v155
	v_pk_fma_f32 v[86:87], v[38:39], v[86:87], v[46:47]
	v_pk_fma_f32 v[88:89], v[40:41], v[88:89], v[48:49]
	global_store_dwordx4 v131, v[86:89], s[6:7] offset:1024
	s_waitcnt vmcnt(15)
	v_pk_add_f32 v[184:185], v[184:185], 1.0 op_sel_hi:[1,0]
	v_pk_add_f32 v[186:187], v[186:187], 1.0 op_sel_hi:[1,0]
	v_pk_fma_f32 v[184:185], v[184:185], v[86:87], v[240:241]
	v_pk_fma_f32 v[186:187], v[186:187], v[88:89], v[242:243]
	v_cvt_pk_bf16_f32 v184, v184, v185
	v_cvt_pk_bf16_f32 v185, v186, v187
	global_store_dwordx2 v117, v[184:185], s[10:11] offset:2560
	v_mul_f32_e32 v90, v90, v155
	v_mul_f32_e32 v91, v91, v155
	v_mul_f32_e32 v92, v92, v155
	v_mul_f32_e32 v93, v93, v155
	v_pk_fma_f32 v[90:91], v[50:51], v[90:91], v[58:59]
	v_pk_fma_f32 v[92:93], v[52:53], v[92:93], v[60:61]
	global_store_dwordx4 v131, v[90:93], s[6:7] offset:2048
	s_waitcnt vmcnt(15)
	v_pk_add_f32 v[212:213], v[212:213], 1.0 op_sel_hi:[1,0]
	v_pk_add_f32 v[214:215], v[214:215], 1.0 op_sel_hi:[1,0]
	v_pk_fma_f32 v[212:213], v[212:213], v[90:91], v[244:245]
	v_pk_fma_f32 v[214:215], v[214:215], v[92:93], v[246:247]
	v_cvt_pk_bf16_f32 v212, v212, v213
	v_cvt_pk_bf16_f32 v213, v214, v215
	global_store_dwordx2 v117, v[212:213], s[10:11] offset:3072
	v_mul_f32_e32 v94, v94, v155
	v_mul_f32_e32 v95, v95, v155
	v_mul_f32_e32 v96, v96, v155
	v_mul_f32_e32 v97, v97, v155
	v_pk_fma_f32 v[94:95], v[54:55], v[94:95], v[62:63]
	v_pk_fma_f32 v[96:97], v[56:57], v[96:97], v[64:65]
	global_store_dwordx4 v131, v[94:97], s[6:7] offset:3072
	s_waitcnt vmcnt(15)
	v_pk_add_f32 v[216:217], v[216:217], 1.0 op_sel_hi:[1,0]
	v_pk_add_f32 v[218:219], v[218:219], 1.0 op_sel_hi:[1,0]
	v_pk_fma_f32 v[216:217], v[216:217], v[94:95], v[248:249]
	v_pk_fma_f32 v[218:219], v[218:219], v[96:97], v[250:251]
	v_cvt_pk_bf16_f32 v216, v216, v217
	v_cvt_pk_bf16_f32 v217, v218, v219
	global_store_dwordx2 v117, v[216:217], s[10:11] offset:3584
	s_add_i32 s0, s68, 0x800
	s_lshl_b32 s1, s0, 13
	s_add_u32 s6, s40, s1
	s_addc_u32 s7, s41, 0
	s_lshl_b32 s1, s0, 12
	s_add_u32 s10, s44, s1
	s_addc_u32 s11, s45, 0
	s_lshr_b32 s1, s0, 11
	s_lshl_b32 s1, s1, 16
	s_add_u32 s16, s14, s1
	s_addc_u32 s17, s15, 0
	global_load_dwordx4 v[66:69], v129, s[6:7]
	global_load_dwordx4 v[70:73], v129, s[6:7] offset:1024
	global_load_dwordx4 v[74:77], v129, s[6:7] offset:2048
	global_load_dwordx4 v[78:81], v129, s[6:7] offset:3072
	global_load_dwordx4 v[82:85], v131, s[6:7]
	global_load_dwordx4 v[86:89], v131, s[6:7] offset:1024
	global_load_dwordx4 v[90:93], v131, s[6:7] offset:2048
	global_load_dwordx4 v[94:97], v131, s[6:7] offset:3072
	v_lshlrev_b32_e32 v151, 2, v116
	global_load_dwordx4 v[158:161], v151, s[16:17]
	v_lshlrev_b32_e32 v151, 2, v118
	global_load_dwordx4 v[220:223], v151, s[16:17]
	v_lshlrev_b32_e32 v151, 2, v120
	global_load_dwordx4 v[162:165], v151, s[16:17]
	v_lshlrev_b32_e32 v151, 2, v122
	global_load_dwordx4 v[224:227], v151, s[16:17]
	v_lshlrev_b32_e32 v151, 2, v124
	global_load_dwordx4 v[166:169], v151, s[16:17]
	v_lshlrev_b32_e32 v151, 2, v126
	global_load_dwordx4 v[228:231], v151, s[16:17]
	v_lshlrev_b32_e32 v151, 2, v128
	global_load_dwordx4 v[176:179], v151, s[16:17]
	v_lshlrev_b32_e32 v151, 2, v130
	global_load_dwordx4 v[232:235], v151, s[16:17]
	v_lshlrev_b32_e32 v151, 2, v132
	global_load_dwordx4 v[180:183], v151, s[16:17]
	v_lshlrev_b32_e32 v151, 2, v134
	global_load_dwordx4 v[236:239], v151, s[16:17]
	v_lshlrev_b32_e32 v151, 2, v136
	global_load_dwordx4 v[184:187], v151, s[16:17]
	v_lshlrev_b32_e32 v151, 2, v138
	global_load_dwordx4 v[240:243], v151, s[16:17]
	v_lshlrev_b32_e32 v151, 2, v140
	global_load_dwordx4 v[212:215], v151, s[16:17]
	v_lshlrev_b32_e32 v151, 2, v142
	global_load_dwordx4 v[244:247], v151, s[16:17]
	v_lshlrev_b32_e32 v151, 2, v144
	global_load_dwordx4 v[216:219], v151, s[16:17]
	v_lshlrev_b32_e32 v151, 2, v146
	global_load_dwordx4 v[248:251], v151, s[16:17]
	s_waitcnt vmcnt(23)
	v_add_f32_e32 v151, v66, v67
	v_add_f32_e32 v155, v68, v69
	v_add_f32_e32 v151, v151, v155
	v_add_f32_e32 v153, 0, v151
	s_waitcnt vmcnt(22)
	v_add_f32_e32 v151, v70, v71
	v_add_f32_e32 v155, v72, v73
	v_add_f32_e32 v151, v151, v155
	v_add_f32_e32 v153, v153, v151
	s_waitcnt vmcnt(21)
	v_add_f32_e32 v151, v74, v75
	v_add_f32_e32 v155, v76, v77
	v_add_f32_e32 v151, v151, v155
	v_add_f32_e32 v153, v153, v151
	s_waitcnt vmcnt(20)
	v_add_f32_e32 v151, v78, v79
	v_add_f32_e32 v155, v80, v81
	v_add_f32_e32 v151, v151, v155
	v_add_f32_e32 v153, v153, v151
	s_waitcnt vmcnt(19)
	v_add_f32_e32 v151, v82, v83
	v_add_f32_e32 v155, v84, v85
	v_add_f32_e32 v151, v151, v155
	v_add_f32_e32 v153, v153, v151
	s_waitcnt vmcnt(18)
	v_add_f32_e32 v151, v86, v87
	v_add_f32_e32 v155, v88, v89
	v_add_f32_e32 v151, v151, v155
	v_add_f32_e32 v153, v153, v151
	s_waitcnt vmcnt(17)
	v_add_f32_e32 v151, v90, v91
	v_add_f32_e32 v155, v92, v93
	v_add_f32_e32 v151, v151, v155
	v_add_f32_e32 v153, v153, v151
	s_waitcnt vmcnt(16)
	v_add_f32_e32 v151, v94, v95
	v_add_f32_e32 v155, v96, v97
	v_add_f32_e32 v151, v151, v155
	v_add_f32_e32 v153, v153, v151
	ds_bpermute_b32 v151, v99, v153
	s_waitcnt lgkmcnt(0)
	v_add_f32_e32 v153, v153, v151
	ds_bpermute_b32 v151, v101, v153
	s_waitcnt lgkmcnt(0)
	v_add_f32_e32 v153, v153, v151
	ds_bpermute_b32 v151, v103, v153
	s_waitcnt lgkmcnt(0)
	v_add_f32_e32 v153, v153, v151
	ds_bpermute_b32 v151, v105, v153
	s_waitcnt lgkmcnt(0)
	v_add_f32_e32 v153, v153, v151
	ds_bpermute_b32 v151, v107, v153
	s_waitcnt lgkmcnt(0)
	v_add_f32_e32 v153, v153, v151
	ds_bpermute_b32 v151, v119, v153
	s_waitcnt lgkmcnt(0)
	v_add_f32_e32 v153, v153, v151
	v_fmac_f32_e32 v66, 0xba000000, v153
	v_fmac_f32_e32 v67, 0xba000000, v153
	v_fmac_f32_e32 v68, 0xba000000, v153
	v_fmac_f32_e32 v69, 0xba000000, v153
	v_fmac_f32_e32 v70, 0xba000000, v153
	v_fmac_f32_e32 v71, 0xba000000, v153
	v_fmac_f32_e32 v72, 0xba000000, v153
	v_fmac_f32_e32 v73, 0xba000000, v153
	v_fmac_f32_e32 v74, 0xba000000, v153
	v_fmac_f32_e32 v75, 0xba000000, v153
	v_fmac_f32_e32 v76, 0xba000000, v153
	v_fmac_f32_e32 v77, 0xba000000, v153
	v_fmac_f32_e32 v78, 0xba000000, v153
	v_fmac_f32_e32 v79, 0xba000000, v153
	v_fmac_f32_e32 v80, 0xba000000, v153
	v_fmac_f32_e32 v81, 0xba000000, v153
	v_fmac_f32_e32 v82, 0xba000000, v153
	v_fmac_f32_e32 v83, 0xba000000, v153
	v_fmac_f32_e32 v84, 0xba000000, v153
	v_fmac_f32_e32 v85, 0xba000000, v153
	v_fmac_f32_e32 v86, 0xba000000, v153
	v_fmac_f32_e32 v87, 0xba000000, v153
	v_fmac_f32_e32 v88, 0xba000000, v153
	v_fmac_f32_e32 v89, 0xba000000, v153
	v_fmac_f32_e32 v90, 0xba000000, v153
	v_fmac_f32_e32 v91, 0xba000000, v153
	v_fmac_f32_e32 v92, 0xba000000, v153
	v_fmac_f32_e32 v93, 0xba000000, v153
	v_fmac_f32_e32 v94, 0xba000000, v153
	v_fmac_f32_e32 v95, 0xba000000, v153
	v_fmac_f32_e32 v96, 0xba000000, v153
	v_fmac_f32_e32 v97, 0xba000000, v153
	v_mul_f32_e32 v151, v67, v67
	v_fma_f32 v151, v66, v66, v151
	v_mul_f32_e32 v155, v69, v69
	v_fma_f32 v155, v68, v68, v155
	v_add_f32_e32 v151, v151, v155
	v_add_f32_e32 v157, 0, v151
	v_mul_f32_e32 v151, v71, v71
	v_fma_f32 v151, v70, v70, v151
	v_mul_f32_e32 v155, v73, v73
	v_fma_f32 v155, v72, v72, v155
	v_add_f32_e32 v151, v151, v155
	v_add_f32_e32 v157, v157, v151
	v_mul_f32_e32 v151, v75, v75
	v_fma_f32 v151, v74, v74, v151
	v_mul_f32_e32 v155, v77, v77
	v_fma_f32 v155, v76, v76, v155
	v_add_f32_e32 v151, v151, v155
	v_add_f32_e32 v157, v157, v151
	v_mul_f32_e32 v151, v79, v79
	v_fma_f32 v151, v78, v78, v151
	v_mul_f32_e32 v155, v81, v81
	v_fma_f32 v155, v80, v80, v155
	v_add_f32_e32 v151, v151, v155
	v_add_f32_e32 v157, v157, v151
	v_mul_f32_e32 v151, v83, v83
	v_fma_f32 v151, v82, v82, v151
	v_mul_f32_e32 v155, v85, v85
	v_fma_f32 v155, v84, v84, v155
	v_add_f32_e32 v151, v151, v155
	v_add_f32_e32 v157, v157, v151
	v_mul_f32_e32 v151, v87, v87
	v_fma_f32 v151, v86, v86, v151
	v_mul_f32_e32 v155, v89, v89
	v_fma_f32 v155, v88, v88, v155
	v_add_f32_e32 v151, v151, v155
	v_add_f32_e32 v157, v157, v151
	v_mul_f32_e32 v151, v91, v91
	v_fma_f32 v151, v90, v90, v151
	v_mul_f32_e32 v155, v93, v93
	v_fma_f32 v155, v92, v92, v155
	v_add_f32_e32 v151, v151, v155
	v_add_f32_e32 v157, v157, v151
	v_mul_f32_e32 v151, v95, v95
	v_fma_f32 v151, v94, v94, v151
	v_mul_f32_e32 v155, v97, v97
	v_fma_f32 v155, v96, v96, v155
	v_add_f32_e32 v151, v151, v155
	v_add_f32_e32 v157, v157, v151
	ds_bpermute_b32 v151, v99, v157
	s_waitcnt lgkmcnt(0)
	v_add_f32_e32 v157, v157, v151
	ds_bpermute_b32 v151, v101, v157
	s_waitcnt lgkmcnt(0)
	v_add_f32_e32 v157, v157, v151
	ds_bpermute_b32 v151, v103, v157
	s_waitcnt lgkmcnt(0)
	v_add_f32_e32 v157, v157, v151
	ds_bpermute_b32 v151, v105, v157
	s_waitcnt lgkmcnt(0)
	v_add_f32_e32 v157, v157, v151
	ds_bpermute_b32 v151, v107, v157
	s_waitcnt lgkmcnt(0)
	v_add_f32_e32 v157, v157, v151
	ds_bpermute_b32 v151, v119, v157
	s_waitcnt lgkmcnt(0)
	v_add_f32_e32 v157, v157, v151
	v_mov_b32_e32 v254, 0x3727c5ac
	v_fmamk_f32 v157, v157, 0x3a000000, v254
	v_mul_f32_e32 v151, 0x4f800000, v157
	s_mov_b32 s9, 0xf800000
	v_cmp_gt_f32_e32 vcc, s9, v157
	s_nop 1
	v_cndmask_b32_e32 v157, v157, v151, vcc
	v_sqrt_f32_e32 v151, v157
	s_nop 0
	v_add_u32_e32 v203, -1, v151
	v_fma_f32 v204, -v203, v151, v157
	v_cmp_ge_f32_e64 s[88:89], 0, v204
	v_add_u32_e32 v204, 1, v151
	s_nop 0
	v_cndmask_b32_e64 v203, v151, v203, s[88:89]
	v_fma_f32 v151, -v204, v151, v157
	v_cmp_lt_f32_e64 s[88:89], 0, v151
	s_nop 1
	v_cndmask_b32_e64 v151, v203, v204, s[88:89]
	v_mul_f32_e32 v203, 0x37800000, v151
	v_cndmask_b32_e32 v151, v151, v203, vcc
	v_mov_b32_e32 v203, 0x260
	v_cmp_class_f32_e32 vcc, v157, v203
	s_nop 1
	v_cndmask_b32_e32 v157, v151, v157, vcc
	v_div_scale_f32 v151, s[88:89], v157, v157, 1.0
	v_rcp_f32_e32 v203, v151
	s_nop 0
	v_fma_f32 v204, -v151, v203, 1.0
	v_fmac_f32_e32 v203, v204, v203
	v_div_scale_f32 v204, vcc, 1.0, v157, 1.0
	v_mul_f32_e32 v205, v204, v203
	v_fma_f32 v254, -v151, v205, v204
	v_fmac_f32_e32 v205, v254, v203
	v_fma_f32 v151, -v151, v205, v204
	v_div_fmas_f32 v151, v151, v203, v205
	v_div_fixup_f32 v155, v151, v157, 1.0
	v_mul_f32_e32 v66, v66, v155
	v_mul_f32_e32 v67, v67, v155
	v_mul_f32_e32 v68, v68, v155
	v_mul_f32_e32 v69, v69, v155
	v_pk_fma_f32 v[66:67], v[2:3], v[66:67], v[10:11]
	v_pk_fma_f32 v[68:69], v[4:5], v[68:69], v[12:13]
	global_store_dwordx4 v129, v[66:69], s[6:7]
	s_waitcnt vmcnt(15)
	v_pk_add_f32 v[158:159], v[158:159], 1.0 op_sel_hi:[1,0]
	v_pk_add_f32 v[160:161], v[160:161], 1.0 op_sel_hi:[1,0]
	v_pk_fma_f32 v[158:159], v[158:159], v[66:67], v[220:221]
	v_pk_fma_f32 v[160:161], v[160:161], v[68:69], v[222:223]
	v_cvt_pk_bf16_f32 v158, v158, v159
	v_cvt_pk_bf16_f32 v159, v160, v161
	global_store_dwordx2 v117, v[158:159], s[10:11]
	v_mul_f32_e32 v70, v70, v155
	v_mul_f32_e32 v71, v71, v155
	v_mul_f32_e32 v72, v72, v155
	v_mul_f32_e32 v73, v73, v155
	v_pk_fma_f32 v[70:71], v[6:7], v[70:71], v[14:15]
	v_pk_fma_f32 v[72:73], v[8:9], v[72:73], v[16:17]
	global_store_dwordx4 v129, v[70:73], s[6:7] offset:1024
	s_waitcnt vmcnt(15)
	v_pk_add_f32 v[162:163], v[162:163], 1.0 op_sel_hi:[1,0]
	v_pk_add_f32 v[164:165], v[164:165], 1.0 op_sel_hi:[1,0]
	v_pk_fma_f32 v[162:163], v[162:163], v[70:71], v[224:225]
	v_pk_fma_f32 v[164:165], v[164:165], v[72:73], v[226:227]
	v_cvt_pk_bf16_f32 v162, v162, v163
	v_cvt_pk_bf16_f32 v163, v164, v165
	global_store_dwordx2 v117, v[162:163], s[10:11] offset:512
	v_mul_f32_e32 v74, v74, v155
	v_mul_f32_e32 v75, v75, v155
	v_mul_f32_e32 v76, v76, v155
	v_mul_f32_e32 v77, v77, v155
	v_pk_fma_f32 v[74:75], v[18:19], v[74:75], v[26:27]
	v_pk_fma_f32 v[76:77], v[20:21], v[76:77], v[28:29]
	global_store_dwordx4 v129, v[74:77], s[6:7] offset:2048
	s_waitcnt vmcnt(15)
	v_pk_add_f32 v[166:167], v[166:167], 1.0 op_sel_hi:[1,0]
	v_pk_add_f32 v[168:169], v[168:169], 1.0 op_sel_hi:[1,0]
	v_pk_fma_f32 v[166:167], v[166:167], v[74:75], v[228:229]
	v_pk_fma_f32 v[168:169], v[168:169], v[76:77], v[230:231]
	v_cvt_pk_bf16_f32 v166, v166, v167
	v_cvt_pk_bf16_f32 v167, v168, v169
	global_store_dwordx2 v117, v[166:167], s[10:11] offset:1024
	v_mul_f32_e32 v78, v78, v155
	v_mul_f32_e32 v79, v79, v155
	v_mul_f32_e32 v80, v80, v155
	v_mul_f32_e32 v81, v81, v155
	v_pk_fma_f32 v[78:79], v[22:23], v[78:79], v[30:31]
	v_pk_fma_f32 v[80:81], v[24:25], v[80:81], v[32:33]
	global_store_dwordx4 v129, v[78:81], s[6:7] offset:3072
	s_waitcnt vmcnt(15)
	v_pk_add_f32 v[176:177], v[176:177], 1.0 op_sel_hi:[1,0]
	v_pk_add_f32 v[178:179], v[178:179], 1.0 op_sel_hi:[1,0]
	v_pk_fma_f32 v[176:177], v[176:177], v[78:79], v[232:233]
	v_pk_fma_f32 v[178:179], v[178:179], v[80:81], v[234:235]
	v_cvt_pk_bf16_f32 v176, v176, v177
	v_cvt_pk_bf16_f32 v177, v178, v179
	global_store_dwordx2 v117, v[176:177], s[10:11] offset:1536
	v_mul_f32_e32 v82, v82, v155
	v_mul_f32_e32 v83, v83, v155
	v_mul_f32_e32 v84, v84, v155
	v_mul_f32_e32 v85, v85, v155
	v_pk_fma_f32 v[82:83], v[34:35], v[82:83], v[42:43]
	v_pk_fma_f32 v[84:85], v[36:37], v[84:85], v[44:45]
	global_store_dwordx4 v131, v[82:85], s[6:7]
	s_waitcnt vmcnt(15)
	v_pk_add_f32 v[180:181], v[180:181], 1.0 op_sel_hi:[1,0]
	v_pk_add_f32 v[182:183], v[182:183], 1.0 op_sel_hi:[1,0]
	v_pk_fma_f32 v[180:181], v[180:181], v[82:83], v[236:237]
	v_pk_fma_f32 v[182:183], v[182:183], v[84:85], v[238:239]
	v_cvt_pk_bf16_f32 v180, v180, v181
	v_cvt_pk_bf16_f32 v181, v182, v183
	global_store_dwordx2 v117, v[180:181], s[10:11] offset:2048
	v_mul_f32_e32 v86, v86, v155
	v_mul_f32_e32 v87, v87, v155
	v_mul_f32_e32 v88, v88, v155
	v_mul_f32_e32 v89, v89, v155
	v_pk_fma_f32 v[86:87], v[38:39], v[86:87], v[46:47]
	v_pk_fma_f32 v[88:89], v[40:41], v[88:89], v[48:49]
	global_store_dwordx4 v131, v[86:89], s[6:7] offset:1024
	s_waitcnt vmcnt(15)
	v_pk_add_f32 v[184:185], v[184:185], 1.0 op_sel_hi:[1,0]
	v_pk_add_f32 v[186:187], v[186:187], 1.0 op_sel_hi:[1,0]
	v_pk_fma_f32 v[184:185], v[184:185], v[86:87], v[240:241]
	v_pk_fma_f32 v[186:187], v[186:187], v[88:89], v[242:243]
	v_cvt_pk_bf16_f32 v184, v184, v185
	v_cvt_pk_bf16_f32 v185, v186, v187
	global_store_dwordx2 v117, v[184:185], s[10:11] offset:2560
	v_mul_f32_e32 v90, v90, v155
	v_mul_f32_e32 v91, v91, v155
	v_mul_f32_e32 v92, v92, v155
	v_mul_f32_e32 v93, v93, v155
	v_pk_fma_f32 v[90:91], v[50:51], v[90:91], v[58:59]
	v_pk_fma_f32 v[92:93], v[52:53], v[92:93], v[60:61]
	global_store_dwordx4 v131, v[90:93], s[6:7] offset:2048
	s_waitcnt vmcnt(15)
	v_pk_add_f32 v[212:213], v[212:213], 1.0 op_sel_hi:[1,0]
	v_pk_add_f32 v[214:215], v[214:215], 1.0 op_sel_hi:[1,0]
	v_pk_fma_f32 v[212:213], v[212:213], v[90:91], v[244:245]
	v_pk_fma_f32 v[214:215], v[214:215], v[92:93], v[246:247]
	v_cvt_pk_bf16_f32 v212, v212, v213
	v_cvt_pk_bf16_f32 v213, v214, v215
	global_store_dwordx2 v117, v[212:213], s[10:11] offset:3072
	v_mul_f32_e32 v94, v94, v155
	v_mul_f32_e32 v95, v95, v155
	v_mul_f32_e32 v96, v96, v155
	v_mul_f32_e32 v97, v97, v155
	v_pk_fma_f32 v[94:95], v[54:55], v[94:95], v[62:63]
	v_pk_fma_f32 v[96:97], v[56:57], v[96:97], v[64:65]
	global_store_dwordx4 v131, v[94:97], s[6:7] offset:3072
	s_waitcnt vmcnt(15)
	v_pk_add_f32 v[216:217], v[216:217], 1.0 op_sel_hi:[1,0]
	v_pk_add_f32 v[218:219], v[218:219], 1.0 op_sel_hi:[1,0]
	v_pk_fma_f32 v[216:217], v[216:217], v[94:95], v[248:249]
	v_pk_fma_f32 v[218:219], v[218:219], v[96:97], v[250:251]
	v_cvt_pk_bf16_f32 v216, v216, v217
	v_cvt_pk_bf16_f32 v217, v218, v219
	global_store_dwordx2 v117, v[216:217], s[10:11] offset:3584
	s_add_i32 s0, s68, 0x1000
	s_lshl_b32 s1, s0, 13
	s_add_u32 s6, s40, s1
	s_addc_u32 s7, s41, 0
	s_lshl_b32 s1, s0, 12
	s_add_u32 s10, s44, s1
	s_addc_u32 s11, s45, 0
	s_lshr_b32 s1, s0, 11
	s_lshl_b32 s1, s1, 16
	s_add_u32 s16, s14, s1
	s_addc_u32 s17, s15, 0
	global_load_dwordx4 v[66:69], v129, s[6:7]
	global_load_dwordx4 v[70:73], v129, s[6:7] offset:1024
	global_load_dwordx4 v[74:77], v129, s[6:7] offset:2048
	global_load_dwordx4 v[78:81], v129, s[6:7] offset:3072
	global_load_dwordx4 v[82:85], v131, s[6:7]
	global_load_dwordx4 v[86:89], v131, s[6:7] offset:1024
	global_load_dwordx4 v[90:93], v131, s[6:7] offset:2048
	global_load_dwordx4 v[94:97], v131, s[6:7] offset:3072
	v_lshlrev_b32_e32 v151, 2, v116
	global_load_dwordx4 v[158:161], v151, s[16:17]
	v_lshlrev_b32_e32 v151, 2, v118
	global_load_dwordx4 v[220:223], v151, s[16:17]
	v_lshlrev_b32_e32 v151, 2, v120
	global_load_dwordx4 v[162:165], v151, s[16:17]
	v_lshlrev_b32_e32 v151, 2, v122
	global_load_dwordx4 v[224:227], v151, s[16:17]
	v_lshlrev_b32_e32 v151, 2, v124
	global_load_dwordx4 v[166:169], v151, s[16:17]
	v_lshlrev_b32_e32 v151, 2, v126
	global_load_dwordx4 v[228:231], v151, s[16:17]
	v_lshlrev_b32_e32 v151, 2, v128
	global_load_dwordx4 v[176:179], v151, s[16:17]
	v_lshlrev_b32_e32 v151, 2, v130
	global_load_dwordx4 v[232:235], v151, s[16:17]
	v_lshlrev_b32_e32 v151, 2, v132
	global_load_dwordx4 v[180:183], v151, s[16:17]
	v_lshlrev_b32_e32 v151, 2, v134
	global_load_dwordx4 v[236:239], v151, s[16:17]
	v_lshlrev_b32_e32 v151, 2, v136
	global_load_dwordx4 v[184:187], v151, s[16:17]
	v_lshlrev_b32_e32 v151, 2, v138
	global_load_dwordx4 v[240:243], v151, s[16:17]
	v_lshlrev_b32_e32 v151, 2, v140
	global_load_dwordx4 v[212:215], v151, s[16:17]
	v_lshlrev_b32_e32 v151, 2, v142
	global_load_dwordx4 v[244:247], v151, s[16:17]
	v_lshlrev_b32_e32 v151, 2, v144
	global_load_dwordx4 v[216:219], v151, s[16:17]
	v_lshlrev_b32_e32 v151, 2, v146
	global_load_dwordx4 v[248:251], v151, s[16:17]
	s_waitcnt vmcnt(23)
	v_add_f32_e32 v151, v66, v67
	v_add_f32_e32 v155, v68, v69
	v_add_f32_e32 v151, v151, v155
	v_add_f32_e32 v153, 0, v151
	s_waitcnt vmcnt(22)
	v_add_f32_e32 v151, v70, v71
	v_add_f32_e32 v155, v72, v73
	v_add_f32_e32 v151, v151, v155
	v_add_f32_e32 v153, v153, v151
	s_waitcnt vmcnt(21)
	v_add_f32_e32 v151, v74, v75
	v_add_f32_e32 v155, v76, v77
	v_add_f32_e32 v151, v151, v155
	v_add_f32_e32 v153, v153, v151
	s_waitcnt vmcnt(20)
	v_add_f32_e32 v151, v78, v79
	v_add_f32_e32 v155, v80, v81
	v_add_f32_e32 v151, v151, v155
	v_add_f32_e32 v153, v153, v151
	s_waitcnt vmcnt(19)
	v_add_f32_e32 v151, v82, v83
	v_add_f32_e32 v155, v84, v85
	v_add_f32_e32 v151, v151, v155
	v_add_f32_e32 v153, v153, v151
	s_waitcnt vmcnt(18)
	v_add_f32_e32 v151, v86, v87
	v_add_f32_e32 v155, v88, v89
	v_add_f32_e32 v151, v151, v155
	v_add_f32_e32 v153, v153, v151
	s_waitcnt vmcnt(17)
	v_add_f32_e32 v151, v90, v91
	v_add_f32_e32 v155, v92, v93
	v_add_f32_e32 v151, v151, v155
	v_add_f32_e32 v153, v153, v151
	s_waitcnt vmcnt(16)
	v_add_f32_e32 v151, v94, v95
	v_add_f32_e32 v155, v96, v97
	v_add_f32_e32 v151, v151, v155
	v_add_f32_e32 v153, v153, v151
	ds_bpermute_b32 v151, v99, v153
	s_waitcnt lgkmcnt(0)
	v_add_f32_e32 v153, v153, v151
	ds_bpermute_b32 v151, v101, v153
	s_waitcnt lgkmcnt(0)
	v_add_f32_e32 v153, v153, v151
	ds_bpermute_b32 v151, v103, v153
	s_waitcnt lgkmcnt(0)
	v_add_f32_e32 v153, v153, v151
	ds_bpermute_b32 v151, v105, v153
	s_waitcnt lgkmcnt(0)
	v_add_f32_e32 v153, v153, v151
	ds_bpermute_b32 v151, v107, v153
	s_waitcnt lgkmcnt(0)
	v_add_f32_e32 v153, v153, v151
	ds_bpermute_b32 v151, v119, v153
	s_waitcnt lgkmcnt(0)
	v_add_f32_e32 v153, v153, v151
	v_fmac_f32_e32 v66, 0xba000000, v153
	v_fmac_f32_e32 v67, 0xba000000, v153
	v_fmac_f32_e32 v68, 0xba000000, v153
	v_fmac_f32_e32 v69, 0xba000000, v153
	v_fmac_f32_e32 v70, 0xba000000, v153
	v_fmac_f32_e32 v71, 0xba000000, v153
	v_fmac_f32_e32 v72, 0xba000000, v153
	v_fmac_f32_e32 v73, 0xba000000, v153
	v_fmac_f32_e32 v74, 0xba000000, v153
	v_fmac_f32_e32 v75, 0xba000000, v153
	v_fmac_f32_e32 v76, 0xba000000, v153
	v_fmac_f32_e32 v77, 0xba000000, v153
	v_fmac_f32_e32 v78, 0xba000000, v153
	v_fmac_f32_e32 v79, 0xba000000, v153
	v_fmac_f32_e32 v80, 0xba000000, v153
	v_fmac_f32_e32 v81, 0xba000000, v153
	v_fmac_f32_e32 v82, 0xba000000, v153
	v_fmac_f32_e32 v83, 0xba000000, v153
	v_fmac_f32_e32 v84, 0xba000000, v153
	v_fmac_f32_e32 v85, 0xba000000, v153
	v_fmac_f32_e32 v86, 0xba000000, v153
	v_fmac_f32_e32 v87, 0xba000000, v153
	v_fmac_f32_e32 v88, 0xba000000, v153
	v_fmac_f32_e32 v89, 0xba000000, v153
	v_fmac_f32_e32 v90, 0xba000000, v153
	v_fmac_f32_e32 v91, 0xba000000, v153
	v_fmac_f32_e32 v92, 0xba000000, v153
	v_fmac_f32_e32 v93, 0xba000000, v153
	v_fmac_f32_e32 v94, 0xba000000, v153
	v_fmac_f32_e32 v95, 0xba000000, v153
	v_fmac_f32_e32 v96, 0xba000000, v153
	v_fmac_f32_e32 v97, 0xba000000, v153
	v_mul_f32_e32 v151, v67, v67
	v_fma_f32 v151, v66, v66, v151
	v_mul_f32_e32 v155, v69, v69
	v_fma_f32 v155, v68, v68, v155
	v_add_f32_e32 v151, v151, v155
	v_add_f32_e32 v157, 0, v151
	v_mul_f32_e32 v151, v71, v71
	v_fma_f32 v151, v70, v70, v151
	v_mul_f32_e32 v155, v73, v73
	v_fma_f32 v155, v72, v72, v155
	v_add_f32_e32 v151, v151, v155
	v_add_f32_e32 v157, v157, v151
	v_mul_f32_e32 v151, v75, v75
	v_fma_f32 v151, v74, v74, v151
	v_mul_f32_e32 v155, v77, v77
	v_fma_f32 v155, v76, v76, v155
	v_add_f32_e32 v151, v151, v155
	v_add_f32_e32 v157, v157, v151
	v_mul_f32_e32 v151, v79, v79
	v_fma_f32 v151, v78, v78, v151
	v_mul_f32_e32 v155, v81, v81
	v_fma_f32 v155, v80, v80, v155
	v_add_f32_e32 v151, v151, v155
	v_add_f32_e32 v157, v157, v151
	v_mul_f32_e32 v151, v83, v83
	v_fma_f32 v151, v82, v82, v151
	v_mul_f32_e32 v155, v85, v85
	v_fma_f32 v155, v84, v84, v155
	v_add_f32_e32 v151, v151, v155
	v_add_f32_e32 v157, v157, v151
	v_mul_f32_e32 v151, v87, v87
	v_fma_f32 v151, v86, v86, v151
	v_mul_f32_e32 v155, v89, v89
	v_fma_f32 v155, v88, v88, v155
	v_add_f32_e32 v151, v151, v155
	v_add_f32_e32 v157, v157, v151
	v_mul_f32_e32 v151, v91, v91
	v_fma_f32 v151, v90, v90, v151
	v_mul_f32_e32 v155, v93, v93
	v_fma_f32 v155, v92, v92, v155
	v_add_f32_e32 v151, v151, v155
	v_add_f32_e32 v157, v157, v151
	v_mul_f32_e32 v151, v95, v95
	v_fma_f32 v151, v94, v94, v151
	v_mul_f32_e32 v155, v97, v97
	v_fma_f32 v155, v96, v96, v155
	v_add_f32_e32 v151, v151, v155
	v_add_f32_e32 v157, v157, v151
	ds_bpermute_b32 v151, v99, v157
	s_waitcnt lgkmcnt(0)
	v_add_f32_e32 v157, v157, v151
	ds_bpermute_b32 v151, v101, v157
	s_waitcnt lgkmcnt(0)
	v_add_f32_e32 v157, v157, v151
	ds_bpermute_b32 v151, v103, v157
	s_waitcnt lgkmcnt(0)
	v_add_f32_e32 v157, v157, v151
	ds_bpermute_b32 v151, v105, v157
	s_waitcnt lgkmcnt(0)
	v_add_f32_e32 v157, v157, v151
	ds_bpermute_b32 v151, v107, v157
	s_waitcnt lgkmcnt(0)
	v_add_f32_e32 v157, v157, v151
	ds_bpermute_b32 v151, v119, v157
	s_waitcnt lgkmcnt(0)
	v_add_f32_e32 v157, v157, v151
	v_mov_b32_e32 v254, 0x3727c5ac
	v_fmamk_f32 v157, v157, 0x3a000000, v254
	v_mul_f32_e32 v151, 0x4f800000, v157
	s_mov_b32 s9, 0xf800000
	v_cmp_gt_f32_e32 vcc, s9, v157
	s_nop 1
	v_cndmask_b32_e32 v157, v157, v151, vcc
	v_sqrt_f32_e32 v151, v157
	s_nop 0
	v_add_u32_e32 v203, -1, v151
	v_fma_f32 v204, -v203, v151, v157
	v_cmp_ge_f32_e64 s[88:89], 0, v204
	v_add_u32_e32 v204, 1, v151
	s_nop 0
	v_cndmask_b32_e64 v203, v151, v203, s[88:89]
	v_fma_f32 v151, -v204, v151, v157
	v_cmp_lt_f32_e64 s[88:89], 0, v151
	s_nop 1
	v_cndmask_b32_e64 v151, v203, v204, s[88:89]
	v_mul_f32_e32 v203, 0x37800000, v151
	v_cndmask_b32_e32 v151, v151, v203, vcc
	v_mov_b32_e32 v203, 0x260
	v_cmp_class_f32_e32 vcc, v157, v203
	s_nop 1
	v_cndmask_b32_e32 v157, v151, v157, vcc
	v_div_scale_f32 v151, s[88:89], v157, v157, 1.0
	v_rcp_f32_e32 v203, v151
	s_nop 0
	v_fma_f32 v204, -v151, v203, 1.0
	v_fmac_f32_e32 v203, v204, v203
	v_div_scale_f32 v204, vcc, 1.0, v157, 1.0
	v_mul_f32_e32 v205, v204, v203
	v_fma_f32 v254, -v151, v205, v204
	v_fmac_f32_e32 v205, v254, v203
	v_fma_f32 v151, -v151, v205, v204
	v_div_fmas_f32 v151, v151, v203, v205
	v_div_fixup_f32 v155, v151, v157, 1.0
	v_mul_f32_e32 v66, v66, v155
	v_mul_f32_e32 v67, v67, v155
	v_mul_f32_e32 v68, v68, v155
	v_mul_f32_e32 v69, v69, v155
	v_pk_fma_f32 v[66:67], v[2:3], v[66:67], v[10:11]
	v_pk_fma_f32 v[68:69], v[4:5], v[68:69], v[12:13]
	global_store_dwordx4 v129, v[66:69], s[6:7]
	s_waitcnt vmcnt(15)
	v_pk_add_f32 v[158:159], v[158:159], 1.0 op_sel_hi:[1,0]
	v_pk_add_f32 v[160:161], v[160:161], 1.0 op_sel_hi:[1,0]
	v_pk_fma_f32 v[158:159], v[158:159], v[66:67], v[220:221]
	v_pk_fma_f32 v[160:161], v[160:161], v[68:69], v[222:223]
	v_cvt_pk_bf16_f32 v158, v158, v159
	v_cvt_pk_bf16_f32 v159, v160, v161
	global_store_dwordx2 v117, v[158:159], s[10:11]
	v_mul_f32_e32 v70, v70, v155
	v_mul_f32_e32 v71, v71, v155
	v_mul_f32_e32 v72, v72, v155
	v_mul_f32_e32 v73, v73, v155
	v_pk_fma_f32 v[70:71], v[6:7], v[70:71], v[14:15]
	v_pk_fma_f32 v[72:73], v[8:9], v[72:73], v[16:17]
	global_store_dwordx4 v129, v[70:73], s[6:7] offset:1024
	s_waitcnt vmcnt(15)
	v_pk_add_f32 v[162:163], v[162:163], 1.0 op_sel_hi:[1,0]
	v_pk_add_f32 v[164:165], v[164:165], 1.0 op_sel_hi:[1,0]
	v_pk_fma_f32 v[162:163], v[162:163], v[70:71], v[224:225]
	v_pk_fma_f32 v[164:165], v[164:165], v[72:73], v[226:227]
	v_cvt_pk_bf16_f32 v162, v162, v163
	v_cvt_pk_bf16_f32 v163, v164, v165
	global_store_dwordx2 v117, v[162:163], s[10:11] offset:512
	v_mul_f32_e32 v74, v74, v155
	v_mul_f32_e32 v75, v75, v155
	v_mul_f32_e32 v76, v76, v155
	v_mul_f32_e32 v77, v77, v155
	v_pk_fma_f32 v[74:75], v[18:19], v[74:75], v[26:27]
	v_pk_fma_f32 v[76:77], v[20:21], v[76:77], v[28:29]
	global_store_dwordx4 v129, v[74:77], s[6:7] offset:2048
	s_waitcnt vmcnt(15)
	v_pk_add_f32 v[166:167], v[166:167], 1.0 op_sel_hi:[1,0]
	v_pk_add_f32 v[168:169], v[168:169], 1.0 op_sel_hi:[1,0]
	v_pk_fma_f32 v[166:167], v[166:167], v[74:75], v[228:229]
	v_pk_fma_f32 v[168:169], v[168:169], v[76:77], v[230:231]
	v_cvt_pk_bf16_f32 v166, v166, v167
	v_cvt_pk_bf16_f32 v167, v168, v169
	global_store_dwordx2 v117, v[166:167], s[10:11] offset:1024
	v_mul_f32_e32 v78, v78, v155
	v_mul_f32_e32 v79, v79, v155
	v_mul_f32_e32 v80, v80, v155
	v_mul_f32_e32 v81, v81, v155
	v_pk_fma_f32 v[78:79], v[22:23], v[78:79], v[30:31]
	v_pk_fma_f32 v[80:81], v[24:25], v[80:81], v[32:33]
	global_store_dwordx4 v129, v[78:81], s[6:7] offset:3072
	s_waitcnt vmcnt(15)
	v_pk_add_f32 v[176:177], v[176:177], 1.0 op_sel_hi:[1,0]
	v_pk_add_f32 v[178:179], v[178:179], 1.0 op_sel_hi:[1,0]
	v_pk_fma_f32 v[176:177], v[176:177], v[78:79], v[232:233]
	v_pk_fma_f32 v[178:179], v[178:179], v[80:81], v[234:235]
	v_cvt_pk_bf16_f32 v176, v176, v177
	v_cvt_pk_bf16_f32 v177, v178, v179
	global_store_dwordx2 v117, v[176:177], s[10:11] offset:1536
	v_mul_f32_e32 v82, v82, v155
	v_mul_f32_e32 v83, v83, v155
	v_mul_f32_e32 v84, v84, v155
	v_mul_f32_e32 v85, v85, v155
	v_pk_fma_f32 v[82:83], v[34:35], v[82:83], v[42:43]
	v_pk_fma_f32 v[84:85], v[36:37], v[84:85], v[44:45]
	global_store_dwordx4 v131, v[82:85], s[6:7]
	s_waitcnt vmcnt(15)
	v_pk_add_f32 v[180:181], v[180:181], 1.0 op_sel_hi:[1,0]
	v_pk_add_f32 v[182:183], v[182:183], 1.0 op_sel_hi:[1,0]
	v_pk_fma_f32 v[180:181], v[180:181], v[82:83], v[236:237]
	v_pk_fma_f32 v[182:183], v[182:183], v[84:85], v[238:239]
	v_cvt_pk_bf16_f32 v180, v180, v181
	v_cvt_pk_bf16_f32 v181, v182, v183
	global_store_dwordx2 v117, v[180:181], s[10:11] offset:2048
	v_mul_f32_e32 v86, v86, v155
	v_mul_f32_e32 v87, v87, v155
	v_mul_f32_e32 v88, v88, v155
	v_mul_f32_e32 v89, v89, v155
	v_pk_fma_f32 v[86:87], v[38:39], v[86:87], v[46:47]
	v_pk_fma_f32 v[88:89], v[40:41], v[88:89], v[48:49]
	global_store_dwordx4 v131, v[86:89], s[6:7] offset:1024
	s_waitcnt vmcnt(15)
	v_pk_add_f32 v[184:185], v[184:185], 1.0 op_sel_hi:[1,0]
	v_pk_add_f32 v[186:187], v[186:187], 1.0 op_sel_hi:[1,0]
	v_pk_fma_f32 v[184:185], v[184:185], v[86:87], v[240:241]
	v_pk_fma_f32 v[186:187], v[186:187], v[88:89], v[242:243]
	v_cvt_pk_bf16_f32 v184, v184, v185
	v_cvt_pk_bf16_f32 v185, v186, v187
	global_store_dwordx2 v117, v[184:185], s[10:11] offset:2560
	v_mul_f32_e32 v90, v90, v155
	v_mul_f32_e32 v91, v91, v155
	v_mul_f32_e32 v92, v92, v155
	v_mul_f32_e32 v93, v93, v155
	v_pk_fma_f32 v[90:91], v[50:51], v[90:91], v[58:59]
	v_pk_fma_f32 v[92:93], v[52:53], v[92:93], v[60:61]
	global_store_dwordx4 v131, v[90:93], s[6:7] offset:2048
	s_waitcnt vmcnt(15)
	v_pk_add_f32 v[212:213], v[212:213], 1.0 op_sel_hi:[1,0]
	v_pk_add_f32 v[214:215], v[214:215], 1.0 op_sel_hi:[1,0]
	v_pk_fma_f32 v[212:213], v[212:213], v[90:91], v[244:245]
	v_pk_fma_f32 v[214:215], v[214:215], v[92:93], v[246:247]
	v_cvt_pk_bf16_f32 v212, v212, v213
	v_cvt_pk_bf16_f32 v213, v214, v215
	global_store_dwordx2 v117, v[212:213], s[10:11] offset:3072
	v_mul_f32_e32 v94, v94, v155
	v_mul_f32_e32 v95, v95, v155
	v_mul_f32_e32 v96, v96, v155
	v_mul_f32_e32 v97, v97, v155
	v_pk_fma_f32 v[94:95], v[54:55], v[94:95], v[62:63]
	v_pk_fma_f32 v[96:97], v[56:57], v[96:97], v[64:65]
	global_store_dwordx4 v131, v[94:97], s[6:7] offset:3072
	s_waitcnt vmcnt(15)
	v_pk_add_f32 v[216:217], v[216:217], 1.0 op_sel_hi:[1,0]
	v_pk_add_f32 v[218:219], v[218:219], 1.0 op_sel_hi:[1,0]
	v_pk_fma_f32 v[216:217], v[216:217], v[94:95], v[248:249]
	v_pk_fma_f32 v[218:219], v[218:219], v[96:97], v[250:251]
	v_cvt_pk_bf16_f32 v216, v216, v217
	v_cvt_pk_bf16_f32 v217, v218, v219
	global_store_dwordx2 v117, v[216:217], s[10:11] offset:3584
	s_add_i32 s0, s68, 0x1800
	s_lshl_b32 s1, s0, 13
	s_add_u32 s6, s40, s1
	s_addc_u32 s7, s41, 0
	s_lshl_b32 s1, s0, 12
	s_add_u32 s10, s44, s1
	s_addc_u32 s11, s45, 0
	s_lshr_b32 s1, s0, 11
	s_lshl_b32 s1, s1, 16
	s_add_u32 s16, s14, s1
	s_addc_u32 s17, s15, 0
	global_load_dwordx4 v[66:69], v129, s[6:7]
	global_load_dwordx4 v[70:73], v129, s[6:7] offset:1024
	global_load_dwordx4 v[74:77], v129, s[6:7] offset:2048
	global_load_dwordx4 v[78:81], v129, s[6:7] offset:3072
	global_load_dwordx4 v[82:85], v131, s[6:7]
	global_load_dwordx4 v[86:89], v131, s[6:7] offset:1024
	global_load_dwordx4 v[90:93], v131, s[6:7] offset:2048
	global_load_dwordx4 v[94:97], v131, s[6:7] offset:3072
	v_lshlrev_b32_e32 v151, 2, v116
	global_load_dwordx4 v[158:161], v151, s[16:17]
	v_lshlrev_b32_e32 v151, 2, v118
	global_load_dwordx4 v[220:223], v151, s[16:17]
	v_lshlrev_b32_e32 v151, 2, v120
	global_load_dwordx4 v[162:165], v151, s[16:17]
	v_lshlrev_b32_e32 v151, 2, v122
	global_load_dwordx4 v[224:227], v151, s[16:17]
	v_lshlrev_b32_e32 v151, 2, v124
	global_load_dwordx4 v[166:169], v151, s[16:17]
	v_lshlrev_b32_e32 v151, 2, v126
	global_load_dwordx4 v[228:231], v151, s[16:17]
	v_lshlrev_b32_e32 v151, 2, v128
	global_load_dwordx4 v[176:179], v151, s[16:17]
	v_lshlrev_b32_e32 v151, 2, v130
	global_load_dwordx4 v[232:235], v151, s[16:17]
	v_lshlrev_b32_e32 v151, 2, v132
	global_load_dwordx4 v[180:183], v151, s[16:17]
	v_lshlrev_b32_e32 v151, 2, v134
	global_load_dwordx4 v[236:239], v151, s[16:17]
	v_lshlrev_b32_e32 v151, 2, v136
	global_load_dwordx4 v[184:187], v151, s[16:17]
	v_lshlrev_b32_e32 v151, 2, v138
	global_load_dwordx4 v[240:243], v151, s[16:17]
	v_lshlrev_b32_e32 v151, 2, v140
	global_load_dwordx4 v[212:215], v151, s[16:17]
	v_lshlrev_b32_e32 v151, 2, v142
	global_load_dwordx4 v[244:247], v151, s[16:17]
	v_lshlrev_b32_e32 v151, 2, v144
	global_load_dwordx4 v[216:219], v151, s[16:17]
	v_lshlrev_b32_e32 v151, 2, v146
	global_load_dwordx4 v[248:251], v151, s[16:17]
	s_waitcnt vmcnt(23)
	v_add_f32_e32 v151, v66, v67
	v_add_f32_e32 v155, v68, v69
	v_add_f32_e32 v151, v151, v155
	v_add_f32_e32 v153, 0, v151
	s_waitcnt vmcnt(22)
	v_add_f32_e32 v151, v70, v71
	v_add_f32_e32 v155, v72, v73
	v_add_f32_e32 v151, v151, v155
	v_add_f32_e32 v153, v153, v151
	s_waitcnt vmcnt(21)
	v_add_f32_e32 v151, v74, v75
	v_add_f32_e32 v155, v76, v77
	v_add_f32_e32 v151, v151, v155
	v_add_f32_e32 v153, v153, v151
	s_waitcnt vmcnt(20)
	v_add_f32_e32 v151, v78, v79
	v_add_f32_e32 v155, v80, v81
	v_add_f32_e32 v151, v151, v155
	v_add_f32_e32 v153, v153, v151
	s_waitcnt vmcnt(19)
	v_add_f32_e32 v151, v82, v83
	v_add_f32_e32 v155, v84, v85
	v_add_f32_e32 v151, v151, v155
	v_add_f32_e32 v153, v153, v151
	s_waitcnt vmcnt(18)
	v_add_f32_e32 v151, v86, v87
	v_add_f32_e32 v155, v88, v89
	v_add_f32_e32 v151, v151, v155
	v_add_f32_e32 v153, v153, v151
	s_waitcnt vmcnt(17)
	v_add_f32_e32 v151, v90, v91
	v_add_f32_e32 v155, v92, v93
	v_add_f32_e32 v151, v151, v155
	v_add_f32_e32 v153, v153, v151
	s_waitcnt vmcnt(16)
	v_add_f32_e32 v151, v94, v95
	v_add_f32_e32 v155, v96, v97
	v_add_f32_e32 v151, v151, v155
	v_add_f32_e32 v153, v153, v151
	ds_bpermute_b32 v151, v99, v153
	s_waitcnt lgkmcnt(0)
	v_add_f32_e32 v153, v153, v151
	ds_bpermute_b32 v151, v101, v153
	s_waitcnt lgkmcnt(0)
	v_add_f32_e32 v153, v153, v151
	ds_bpermute_b32 v151, v103, v153
	s_waitcnt lgkmcnt(0)
	v_add_f32_e32 v153, v153, v151
	ds_bpermute_b32 v151, v105, v153
	s_waitcnt lgkmcnt(0)
	v_add_f32_e32 v153, v153, v151
	ds_bpermute_b32 v151, v107, v153
	s_waitcnt lgkmcnt(0)
	v_add_f32_e32 v153, v153, v151
	ds_bpermute_b32 v151, v119, v153
	s_waitcnt lgkmcnt(0)
	v_add_f32_e32 v153, v153, v151
	v_fmac_f32_e32 v66, 0xba000000, v153
	v_fmac_f32_e32 v67, 0xba000000, v153
	v_fmac_f32_e32 v68, 0xba000000, v153
	v_fmac_f32_e32 v69, 0xba000000, v153
	v_fmac_f32_e32 v70, 0xba000000, v153
	v_fmac_f32_e32 v71, 0xba000000, v153
	v_fmac_f32_e32 v72, 0xba000000, v153
	v_fmac_f32_e32 v73, 0xba000000, v153
	v_fmac_f32_e32 v74, 0xba000000, v153
	v_fmac_f32_e32 v75, 0xba000000, v153
	v_fmac_f32_e32 v76, 0xba000000, v153
	v_fmac_f32_e32 v77, 0xba000000, v153
	v_fmac_f32_e32 v78, 0xba000000, v153
	v_fmac_f32_e32 v79, 0xba000000, v153
	v_fmac_f32_e32 v80, 0xba000000, v153
	v_fmac_f32_e32 v81, 0xba000000, v153
	v_fmac_f32_e32 v82, 0xba000000, v153
	v_fmac_f32_e32 v83, 0xba000000, v153
	v_fmac_f32_e32 v84, 0xba000000, v153
	v_fmac_f32_e32 v85, 0xba000000, v153
	v_fmac_f32_e32 v86, 0xba000000, v153
	v_fmac_f32_e32 v87, 0xba000000, v153
	v_fmac_f32_e32 v88, 0xba000000, v153
	v_fmac_f32_e32 v89, 0xba000000, v153
	v_fmac_f32_e32 v90, 0xba000000, v153
	v_fmac_f32_e32 v91, 0xba000000, v153
	v_fmac_f32_e32 v92, 0xba000000, v153
	v_fmac_f32_e32 v93, 0xba000000, v153
	v_fmac_f32_e32 v94, 0xba000000, v153
	v_fmac_f32_e32 v95, 0xba000000, v153
	v_fmac_f32_e32 v96, 0xba000000, v153
	v_fmac_f32_e32 v97, 0xba000000, v153
	v_mul_f32_e32 v151, v67, v67
	v_fma_f32 v151, v66, v66, v151
	v_mul_f32_e32 v155, v69, v69
	v_fma_f32 v155, v68, v68, v155
	v_add_f32_e32 v151, v151, v155
	v_add_f32_e32 v157, 0, v151
	v_mul_f32_e32 v151, v71, v71
	v_fma_f32 v151, v70, v70, v151
	v_mul_f32_e32 v155, v73, v73
	v_fma_f32 v155, v72, v72, v155
	v_add_f32_e32 v151, v151, v155
	v_add_f32_e32 v157, v157, v151
	v_mul_f32_e32 v151, v75, v75
	v_fma_f32 v151, v74, v74, v151
	v_mul_f32_e32 v155, v77, v77
	v_fma_f32 v155, v76, v76, v155
	v_add_f32_e32 v151, v151, v155
	v_add_f32_e32 v157, v157, v151
	v_mul_f32_e32 v151, v79, v79
	v_fma_f32 v151, v78, v78, v151
	v_mul_f32_e32 v155, v81, v81
	v_fma_f32 v155, v80, v80, v155
	v_add_f32_e32 v151, v151, v155
	v_add_f32_e32 v157, v157, v151
	v_mul_f32_e32 v151, v83, v83
	v_fma_f32 v151, v82, v82, v151
	v_mul_f32_e32 v155, v85, v85
	v_fma_f32 v155, v84, v84, v155
	v_add_f32_e32 v151, v151, v155
	v_add_f32_e32 v157, v157, v151
	v_mul_f32_e32 v151, v87, v87
	v_fma_f32 v151, v86, v86, v151
	v_mul_f32_e32 v155, v89, v89
	v_fma_f32 v155, v88, v88, v155
	v_add_f32_e32 v151, v151, v155
	v_add_f32_e32 v157, v157, v151
	v_mul_f32_e32 v151, v91, v91
	v_fma_f32 v151, v90, v90, v151
	v_mul_f32_e32 v155, v93, v93
	v_fma_f32 v155, v92, v92, v155
	v_add_f32_e32 v151, v151, v155
	v_add_f32_e32 v157, v157, v151
	v_mul_f32_e32 v151, v95, v95
	v_fma_f32 v151, v94, v94, v151
	v_mul_f32_e32 v155, v97, v97
	v_fma_f32 v155, v96, v96, v155
	v_add_f32_e32 v151, v151, v155
	v_add_f32_e32 v157, v157, v151
	ds_bpermute_b32 v151, v99, v157
	s_waitcnt lgkmcnt(0)
	v_add_f32_e32 v157, v157, v151
	ds_bpermute_b32 v151, v101, v157
	s_waitcnt lgkmcnt(0)
	v_add_f32_e32 v157, v157, v151
	ds_bpermute_b32 v151, v103, v157
	s_waitcnt lgkmcnt(0)
	v_add_f32_e32 v157, v157, v151
	ds_bpermute_b32 v151, v105, v157
	s_waitcnt lgkmcnt(0)
	v_add_f32_e32 v157, v157, v151
	ds_bpermute_b32 v151, v107, v157
	s_waitcnt lgkmcnt(0)
	v_add_f32_e32 v157, v157, v151
	ds_bpermute_b32 v151, v119, v157
	s_waitcnt lgkmcnt(0)
	v_add_f32_e32 v157, v157, v151
	v_mov_b32_e32 v254, 0x3727c5ac
	v_fmamk_f32 v157, v157, 0x3a000000, v254
	v_mul_f32_e32 v151, 0x4f800000, v157
	s_mov_b32 s9, 0xf800000
	v_cmp_gt_f32_e32 vcc, s9, v157
	s_nop 1
	v_cndmask_b32_e32 v157, v157, v151, vcc
	v_sqrt_f32_e32 v151, v157
	s_nop 0
	v_add_u32_e32 v203, -1, v151
	v_fma_f32 v204, -v203, v151, v157
	v_cmp_ge_f32_e64 s[88:89], 0, v204
	v_add_u32_e32 v204, 1, v151
	s_nop 0
	v_cndmask_b32_e64 v203, v151, v203, s[88:89]
	v_fma_f32 v151, -v204, v151, v157
	v_cmp_lt_f32_e64 s[88:89], 0, v151
	s_nop 1
	v_cndmask_b32_e64 v151, v203, v204, s[88:89]
	v_mul_f32_e32 v203, 0x37800000, v151
	v_cndmask_b32_e32 v151, v151, v203, vcc
	v_mov_b32_e32 v203, 0x260
	v_cmp_class_f32_e32 vcc, v157, v203
	s_nop 1
	v_cndmask_b32_e32 v157, v151, v157, vcc
	v_div_scale_f32 v151, s[88:89], v157, v157, 1.0
	v_rcp_f32_e32 v203, v151
	s_nop 0
	v_fma_f32 v204, -v151, v203, 1.0
	v_fmac_f32_e32 v203, v204, v203
	v_div_scale_f32 v204, vcc, 1.0, v157, 1.0
	v_mul_f32_e32 v205, v204, v203
	v_fma_f32 v254, -v151, v205, v204
	v_fmac_f32_e32 v205, v254, v203
	v_fma_f32 v151, -v151, v205, v204
	v_div_fmas_f32 v151, v151, v203, v205
	v_div_fixup_f32 v155, v151, v157, 1.0
	v_mul_f32_e32 v66, v66, v155
	v_mul_f32_e32 v67, v67, v155
	v_mul_f32_e32 v68, v68, v155
	v_mul_f32_e32 v69, v69, v155
	v_pk_fma_f32 v[66:67], v[2:3], v[66:67], v[10:11]
	v_pk_fma_f32 v[68:69], v[4:5], v[68:69], v[12:13]
	global_store_dwordx4 v129, v[66:69], s[6:7]
	s_waitcnt vmcnt(15)
	v_pk_add_f32 v[158:159], v[158:159], 1.0 op_sel_hi:[1,0]
	v_pk_add_f32 v[160:161], v[160:161], 1.0 op_sel_hi:[1,0]
	v_pk_fma_f32 v[158:159], v[158:159], v[66:67], v[220:221]
	v_pk_fma_f32 v[160:161], v[160:161], v[68:69], v[222:223]
	v_cvt_pk_bf16_f32 v158, v158, v159
	v_cvt_pk_bf16_f32 v159, v160, v161
	global_store_dwordx2 v117, v[158:159], s[10:11]
	v_mul_f32_e32 v70, v70, v155
	v_mul_f32_e32 v71, v71, v155
	v_mul_f32_e32 v72, v72, v155
	v_mul_f32_e32 v73, v73, v155
	v_pk_fma_f32 v[70:71], v[6:7], v[70:71], v[14:15]
	v_pk_fma_f32 v[72:73], v[8:9], v[72:73], v[16:17]
	global_store_dwordx4 v129, v[70:73], s[6:7] offset:1024
	s_waitcnt vmcnt(15)
	v_pk_add_f32 v[162:163], v[162:163], 1.0 op_sel_hi:[1,0]
	v_pk_add_f32 v[164:165], v[164:165], 1.0 op_sel_hi:[1,0]
	v_pk_fma_f32 v[162:163], v[162:163], v[70:71], v[224:225]
	v_pk_fma_f32 v[164:165], v[164:165], v[72:73], v[226:227]
	v_cvt_pk_bf16_f32 v162, v162, v163
	v_cvt_pk_bf16_f32 v163, v164, v165
	global_store_dwordx2 v117, v[162:163], s[10:11] offset:512
	v_mul_f32_e32 v74, v74, v155
	v_mul_f32_e32 v75, v75, v155
	v_mul_f32_e32 v76, v76, v155
	v_mul_f32_e32 v77, v77, v155
	v_pk_fma_f32 v[74:75], v[18:19], v[74:75], v[26:27]
	v_pk_fma_f32 v[76:77], v[20:21], v[76:77], v[28:29]
	global_store_dwordx4 v129, v[74:77], s[6:7] offset:2048
	s_waitcnt vmcnt(15)
	v_pk_add_f32 v[166:167], v[166:167], 1.0 op_sel_hi:[1,0]
	v_pk_add_f32 v[168:169], v[168:169], 1.0 op_sel_hi:[1,0]
	v_pk_fma_f32 v[166:167], v[166:167], v[74:75], v[228:229]
	v_pk_fma_f32 v[168:169], v[168:169], v[76:77], v[230:231]
	v_cvt_pk_bf16_f32 v166, v166, v167
	v_cvt_pk_bf16_f32 v167, v168, v169
	global_store_dwordx2 v117, v[166:167], s[10:11] offset:1024
	v_mul_f32_e32 v78, v78, v155
	v_mul_f32_e32 v79, v79, v155
	v_mul_f32_e32 v80, v80, v155
	v_mul_f32_e32 v81, v81, v155
	v_pk_fma_f32 v[78:79], v[22:23], v[78:79], v[30:31]
	v_pk_fma_f32 v[80:81], v[24:25], v[80:81], v[32:33]
	global_store_dwordx4 v129, v[78:81], s[6:7] offset:3072
	s_waitcnt vmcnt(15)
	v_pk_add_f32 v[176:177], v[176:177], 1.0 op_sel_hi:[1,0]
	v_pk_add_f32 v[178:179], v[178:179], 1.0 op_sel_hi:[1,0]
	v_pk_fma_f32 v[176:177], v[176:177], v[78:79], v[232:233]
	v_pk_fma_f32 v[178:179], v[178:179], v[80:81], v[234:235]
	v_cvt_pk_bf16_f32 v176, v176, v177
	v_cvt_pk_bf16_f32 v177, v178, v179
	global_store_dwordx2 v117, v[176:177], s[10:11] offset:1536
	v_mul_f32_e32 v82, v82, v155
	v_mul_f32_e32 v83, v83, v155
	v_mul_f32_e32 v84, v84, v155
	v_mul_f32_e32 v85, v85, v155
	v_pk_fma_f32 v[82:83], v[34:35], v[82:83], v[42:43]
	v_pk_fma_f32 v[84:85], v[36:37], v[84:85], v[44:45]
	global_store_dwordx4 v131, v[82:85], s[6:7]
	s_waitcnt vmcnt(15)
	v_pk_add_f32 v[180:181], v[180:181], 1.0 op_sel_hi:[1,0]
	v_pk_add_f32 v[182:183], v[182:183], 1.0 op_sel_hi:[1,0]
	v_pk_fma_f32 v[180:181], v[180:181], v[82:83], v[236:237]
	v_pk_fma_f32 v[182:183], v[182:183], v[84:85], v[238:239]
	v_cvt_pk_bf16_f32 v180, v180, v181
	v_cvt_pk_bf16_f32 v181, v182, v183
	global_store_dwordx2 v117, v[180:181], s[10:11] offset:2048
	v_mul_f32_e32 v86, v86, v155
	v_mul_f32_e32 v87, v87, v155
	v_mul_f32_e32 v88, v88, v155
	v_mul_f32_e32 v89, v89, v155
	v_pk_fma_f32 v[86:87], v[38:39], v[86:87], v[46:47]
	v_pk_fma_f32 v[88:89], v[40:41], v[88:89], v[48:49]
	global_store_dwordx4 v131, v[86:89], s[6:7] offset:1024
	s_waitcnt vmcnt(15)
	v_pk_add_f32 v[184:185], v[184:185], 1.0 op_sel_hi:[1,0]
	v_pk_add_f32 v[186:187], v[186:187], 1.0 op_sel_hi:[1,0]
	v_pk_fma_f32 v[184:185], v[184:185], v[86:87], v[240:241]
	v_pk_fma_f32 v[186:187], v[186:187], v[88:89], v[242:243]
	v_cvt_pk_bf16_f32 v184, v184, v185
	v_cvt_pk_bf16_f32 v185, v186, v187
	global_store_dwordx2 v117, v[184:185], s[10:11] offset:2560
	v_mul_f32_e32 v90, v90, v155
	v_mul_f32_e32 v91, v91, v155
	v_mul_f32_e32 v92, v92, v155
	v_mul_f32_e32 v93, v93, v155
	v_pk_fma_f32 v[90:91], v[50:51], v[90:91], v[58:59]
	v_pk_fma_f32 v[92:93], v[52:53], v[92:93], v[60:61]
	global_store_dwordx4 v131, v[90:93], s[6:7] offset:2048
	s_waitcnt vmcnt(15)
	v_pk_add_f32 v[212:213], v[212:213], 1.0 op_sel_hi:[1,0]
	v_pk_add_f32 v[214:215], v[214:215], 1.0 op_sel_hi:[1,0]
	v_pk_fma_f32 v[212:213], v[212:213], v[90:91], v[244:245]
	v_pk_fma_f32 v[214:215], v[214:215], v[92:93], v[246:247]
	v_cvt_pk_bf16_f32 v212, v212, v213
	v_cvt_pk_bf16_f32 v213, v214, v215
	global_store_dwordx2 v117, v[212:213], s[10:11] offset:3072
	v_mul_f32_e32 v94, v94, v155
	v_mul_f32_e32 v95, v95, v155
	v_mul_f32_e32 v96, v96, v155
	v_mul_f32_e32 v97, v97, v155
	v_pk_fma_f32 v[94:95], v[54:55], v[94:95], v[62:63]
	v_pk_fma_f32 v[96:97], v[56:57], v[96:97], v[64:65]
	global_store_dwordx4 v131, v[94:97], s[6:7] offset:3072
	s_waitcnt vmcnt(15)
	v_pk_add_f32 v[216:217], v[216:217], 1.0 op_sel_hi:[1,0]
	v_pk_add_f32 v[218:219], v[218:219], 1.0 op_sel_hi:[1,0]
	v_pk_fma_f32 v[216:217], v[216:217], v[94:95], v[248:249]
	v_pk_fma_f32 v[218:219], v[218:219], v[96:97], v[250:251]
	v_cvt_pk_bf16_f32 v216, v216, v217
	v_cvt_pk_bf16_f32 v217, v218, v219
	global_store_dwordx2 v117, v[216:217], s[10:11] offset:3584
	s_cmp_gt_u32 s2, 127
	s_cbranch_scc1 .Lp6_nosample
	s_waitcnt vmcnt(0)
	v_readlane_b32 s0, v255, 5
	s_lshl_b32 s9, s0, 10
	v_add_u32_e32 v73, s9, v129
	s_lshl_b32 s9, s0, 9
	v_add_u32_e32 v74, s9, v117
	s_lshl_b32 s9, s2, 13
	s_add_u32 s32, s42, s9
	s_addc_u32 s33, s43, 0
	s_add_u32 s50, s32, 0x100000
	s_addc_u32 s51, s33, 0
	s_add_u32 s52, s50, 0x100000
	s_addc_u32 s53, s51, 0
	s_add_u32 s54, s52, 0x100000
	s_addc_u32 s55, s53, 0
	s_add_u32 s56, s54, 0x100000
	s_addc_u32 s57, s55, 0
	s_add_u32 s60, s56, 0x100000
	s_addc_u32 s61, s57, 0
	s_add_u32 s62, s60, 0x100000
	s_addc_u32 s63, s61, 0
	s_add_u32 s74, s62, 0x100000
	s_addc_u32 s75, s63, 0
	v_readfirstlane_b32 s86, v114
	v_readfirstlane_b32 s87, v115
	s_add_u32 s86, s86, s9
	s_addc_u32 s87, s87, 0
	s_add_i32 s16, s2, 4
	s_lshl_b32 s16, s16, 16
	s_add_u32 s16, s14, s16
	s_addc_u32 s17, s15, 0
	s_add_i32 s0, s2, 0x2000
	s_lshl_b32 s1, s0, 13
	s_add_u32 s6, s40, s1
	s_addc_u32 s7, s41, 0
	s_lshl_b32 s1, s0, 12
	s_add_u32 s10, s44, s1
	s_addc_u32 s11, s45, 0
	v_readlane_b32 s9, v255, 5
	s_lshl_b32 s1, s9, 6
	v_readlane_b32 s90, v255, 0
	v_readlane_b32 s91, v255, 1
	s_sub_u32 s90, s90, 0xc8
	s_subb_u32 s91, s91, 0
	s_load_dwordx2 s[94:95], s[90:91], 0x78
	s_load_dwordx2 s[88:89], s[90:91], 0x80
	v_add_u32_e32 v70, s1, v170
	v_add_u32_e32 v70, 0x400, v70
	v_mul_u32_u24_e32 v151, 0x1556, v70
	v_lshrrev_b32_e32 v151, 16, v151
	v_lshlrev_b32_e32 v70, 4, v70
	v_lshl_add_u32 v70, v151, 6, v70
	v_add_u32_e32 v71, s1, v170
	v_add_u32_e32 v71, 0x800, v71
	v_mul_u32_u24_e32 v151, 0x1556, v71
	v_lshrrev_b32_e32 v151, 16, v151
	v_lshlrev_b32_e32 v71, 4, v71
	v_lshl_add_u32 v71, v151, 6, v71
	v_add_u32_e32 v72, s1, v170
	v_add_u32_e32 v72, 0x600, v72
	v_mul_u32_u24_e32 v151, 0x1556, v72
	v_lshrrev_b32_e32 v151, 16, v151
	v_lshlrev_b32_e32 v72, 4, v72
	v_lshl_add_u32 v72, v151, 6, v72
	global_load_dwordx4 v[158:161], v73, s[32:33]
	global_load_dwordx4 v[162:165], v73, s[50:51]
	global_load_dwordx4 v[166:169], v73, s[52:53]
	global_load_dwordx4 v[176:179], v73, s[54:55]
	global_load_dwordx4 v[180:183], v73, s[56:57]
	global_load_dwordx4 v[184:187], v73, s[60:61]
	global_load_dwordx4 v[212:215], v73, s[62:63]
	global_load_dwordx4 v[216:219], v73, s[74:75]
	global_load_dwordx4 v[224:227], v70, s[16:17]
	global_load_dwordx4 v[220:223], v73, s[86:87]
	global_load_dwordx4 v[228:231], v71, s[16:17]
	global_load_dwordx4 v[232:235], v72, s[16:17]
	s_waitcnt lgkmcnt(0)
	global_load_dwordx4 v[236:239], v73, s[94:95]
	global_load_dwordx4 v[240:243], v73, s[88:89]
	s_waitcnt vmcnt(13)
	v_pk_add_f32 v[252:253], v[158:159], 0 op_sel_hi:[1,0]
	v_pk_add_f32 v[148:149], v[160:161], 0 op_sel_hi:[1,0]
	s_waitcnt vmcnt(12)
	v_pk_add_f32 v[252:253], v[252:253], v[162:163]
	v_pk_add_f32 v[148:149], v[148:149], v[164:165]
	s_waitcnt vmcnt(11)
	v_pk_add_f32 v[252:253], v[252:253], v[166:167]
	v_pk_add_f32 v[148:149], v[148:149], v[168:169]
	s_waitcnt vmcnt(10)
	v_pk_add_f32 v[252:253], v[252:253], v[176:177]
	v_pk_add_f32 v[148:149], v[148:149], v[178:179]
	s_waitcnt vmcnt(9)
	v_pk_add_f32 v[252:253], v[252:253], v[180:181]
	v_pk_add_f32 v[148:149], v[148:149], v[182:183]
	s_waitcnt vmcnt(8)
	v_pk_add_f32 v[252:253], v[252:253], v[184:185]
	v_pk_add_f32 v[148:149], v[148:149], v[186:187]
	s_waitcnt vmcnt(7)
	v_pk_add_f32 v[252:253], v[252:253], v[212:213]
	v_pk_add_f32 v[148:149], v[148:149], v[214:215]
	s_waitcnt vmcnt(6)
	v_pk_add_f32 v[252:253], v[252:253], v[216:217]
	v_pk_add_f32 v[148:149], v[148:149], v[218:219]
	s_waitcnt vmcnt(5)
	v_pk_mul_f32 v[252:253], v[252:253], v[224:225]
	v_pk_mul_f32 v[148:149], v[148:149], v[226:227]
	s_waitcnt vmcnt(4)
	v_fma_f32 v66, v220, s3, v252
	v_fma_f32 v67, v221, s3, v253
	v_fma_f32 v68, v222, s3, v148
	v_fma_f32 v69, v223, s3, v149
	v_add_f32_e32 v151, v66, v67
	v_add_f32_e32 v155, v68, v69
	v_add_f32_e32 v153, v151, v155
	ds_bpermute_b32 v151, v99, v153
	s_waitcnt lgkmcnt(0)
	v_add_f32_e32 v153, v153, v151
	ds_bpermute_b32 v151, v101, v153
	s_waitcnt lgkmcnt(0)
	v_add_f32_e32 v153, v153, v151
	ds_bpermute_b32 v151, v103, v153
	s_waitcnt lgkmcnt(0)
	v_add_f32_e32 v153, v153, v151
	ds_bpermute_b32 v151, v105, v153
	s_waitcnt lgkmcnt(0)
	v_add_f32_e32 v153, v153, v151
	ds_bpermute_b32 v151, v107, v153
	s_waitcnt lgkmcnt(0)
	v_add_f32_e32 v153, v153, v151
	ds_bpermute_b32 v151, v119, v153
	s_waitcnt lgkmcnt(0)
	v_add_f32_e32 v153, v153, v151
	v_readlane_b32 s0, v255, 5
	s_lshl_b32 s0, s0, 2
	s_add_i32 s0, s0, 0x20040
	v_mov_b32_e32 v203, s0
	ds_write_b32 v203, v153
	s_waitcnt lgkmcnt(0)
	s_barrier
	v_mov_b32_e32 v204, 0x20040
	ds_read_b128 v[158:161], v204
	ds_read_b128 v[162:165], v204 offset:16
	s_waitcnt lgkmcnt(0)
	v_add_f32_e32 v153, 0, v158
	v_add_f32_e32 v153, v153, v159
	v_add_f32_e32 v153, v153, v160
	v_add_f32_e32 v153, v153, v161
	v_add_f32_e32 v153, v153, v162
	v_add_f32_e32 v153, v153, v163
	v_add_f32_e32 v153, v153, v164
	v_add_f32_e32 v153, v153, v165
	v_fmac_f32_e32 v66, 0xba000000, v153
	v_fmac_f32_e32 v67, 0xba000000, v153
	v_fmac_f32_e32 v68, 0xba000000, v153
	v_fmac_f32_e32 v69, 0xba000000, v153
	v_mul_f32_e32 v151, v67, v67
	v_fma_f32 v151, v66, v66, v151
	v_mul_f32_e32 v155, v69, v69
	v_fma_f32 v155, v68, v68, v155
	v_add_f32_e32 v157, v151, v155
	ds_bpermute_b32 v151, v99, v157
	s_waitcnt lgkmcnt(0)
	v_add_f32_e32 v157, v157, v151
	ds_bpermute_b32 v151, v101, v157
	s_waitcnt lgkmcnt(0)
	v_add_f32_e32 v157, v157, v151
	ds_bpermute_b32 v151, v103, v157
	s_waitcnt lgkmcnt(0)
	v_add_f32_e32 v157, v157, v151
	ds_bpermute_b32 v151, v105, v157
	s_waitcnt lgkmcnt(0)
	v_add_f32_e32 v157, v157, v151
	ds_bpermute_b32 v151, v107, v157
	s_waitcnt lgkmcnt(0)
	v_add_f32_e32 v157, v157, v151
	ds_bpermute_b32 v151, v119, v157
	s_waitcnt lgkmcnt(0)
	v_add_f32_e32 v157, v157, v151
	v_add_u32_e32 v203, 32, v203
	ds_write_b32 v203, v157
	s_waitcnt lgkmcnt(0)
	s_barrier
	ds_read_b128 v[158:161], v204 offset:32
	ds_read_b128 v[162:165], v204 offset:48
	s_waitcnt lgkmcnt(0)
	v_add_f32_e32 v157, 0, v158
	v_add_f32_e32 v157, v157, v159
	v_add_f32_e32 v157, v157, v160
	v_add_f32_e32 v157, v157, v161
	v_add_f32_e32 v157, v157, v162
	v_add_f32_e32 v157, v157, v163
	v_add_f32_e32 v157, v157, v164
	v_add_f32_e32 v157, v157, v165
	v_mov_b32_e32 v254, 0x3727c5ac
	v_fmamk_f32 v157, v157, 0x3a000000, v254
	v_mul_f32_e32 v151, 0x4f800000, v157
	s_mov_b32 s9, 0xf800000
	v_cmp_gt_f32_e32 vcc, s9, v157
	s_nop 1
	v_cndmask_b32_e32 v157, v157, v151, vcc
	v_sqrt_f32_e32 v151, v157
	s_nop 0
	v_add_u32_e32 v203, -1, v151
	v_fma_f32 v204, -v203, v151, v157
	v_cmp_ge_f32_e64 s[88:89], 0, v204
	v_add_u32_e32 v204, 1, v151
	s_nop 0
	v_cndmask_b32_e64 v203, v151, v203, s[88:89]
	v_fma_f32 v151, -v204, v151, v157
	v_cmp_lt_f32_e64 s[88:89], 0, v151
	s_nop 1
	v_cndmask_b32_e64 v151, v203, v204, s[88:89]
	v_mul_f32_e32 v203, 0x37800000, v151
	v_cndmask_b32_e32 v151, v151, v203, vcc
	v_mov_b32_e32 v203, 0x260
	v_cmp_class_f32_e32 vcc, v157, v203
	s_nop 1
	v_cndmask_b32_e32 v157, v151, v157, vcc
	v_div_scale_f32 v151, s[88:89], v157, v157, 1.0
	v_rcp_f32_e32 v203, v151
	s_nop 0
	v_fma_f32 v204, -v151, v203, 1.0
	v_fmac_f32_e32 v203, v204, v203
	v_div_scale_f32 v204, vcc, 1.0, v157, 1.0
	v_mul_f32_e32 v205, v204, v203
	v_fma_f32 v254, -v151, v205, v204
	v_fmac_f32_e32 v205, v254, v203
	v_fma_f32 v151, -v151, v205, v204
	v_div_fmas_f32 v151, v151, v203, v205
	v_div_fixup_f32 v155, v151, v157, 1.0
	s_waitcnt vmcnt(0)
	v_mul_f32_e32 v66, v66, v155
	v_mul_f32_e32 v67, v67, v155
	v_mul_f32_e32 v68, v68, v155
	v_mul_f32_e32 v69, v69, v155
	v_pk_fma_f32 v[66:67], v[236:237], v[66:67], v[240:241]
	v_pk_fma_f32 v[68:69], v[238:239], v[68:69], v[242:243]
	global_store_dwordx4 v73, v[66:69], s[6:7]
	v_pk_add_f32 v[228:229], v[228:229], 1.0 op_sel_hi:[1,0]
	v_pk_add_f32 v[230:231], v[230:231], 1.0 op_sel_hi:[1,0]
	v_pk_fma_f32 v[228:229], v[228:229], v[66:67], v[232:233]
	v_pk_fma_f32 v[230:231], v[230:231], v[68:69], v[234:235]
	v_cvt_pk_bf16_f32 v228, v228, v229
	v_cvt_pk_bf16_f32 v229, v230, v231
	global_store_dwordx2 v74, v[228:229], s[10:11]
